# GDN prep forward substitution hand-written: LDS reads of row i+1 issued before the FMAs of row i (two register banks), same FMA chains and summation order
# speedup vs baseline: 1.0143x; 1.0080x over previous
.LBB0_867:
	s_or_b64 exec, exec, s[4:5]
	v_sub_f32_e32 v18, v46, v45
	v_mul_f32_e32 v18, 0x3fb8aa3b, v18
	v_exp_f32_e32 v18, v18
	v_mul_u32_u24_e32 v19, 0x880, v105
	s_waitcnt lgkmcnt(0)
	s_barrier
	v_mul_f32_e32 v0, v18, v0
	v_mul_f32_e32 v1, v18, v1
	v_mul_f32_e32 v2, v18, v2
	v_mul_f32_e32 v3, v18, v3
	v_mul_f32_e32 v4, v18, v4
	v_mul_f32_e32 v5, v18, v5
	v_mul_f32_e32 v6, v18, v6
	v_mul_f32_e32 v7, v18, v7
	v_mul_f32_e32 v8, v18, v8
	v_mul_f32_e32 v9, v18, v9
	v_mul_f32_e32 v10, v18, v10
	v_mul_f32_e32 v11, v18, v11
	v_mul_f32_e32 v12, v18, v12
	v_mul_f32_e32 v13, v18, v13
	v_mul_f32_e32 v14, v18, v14
	v_mul_f32_e32 v15, v18, v15
	v_lshlrev_b32_e32 v18, 1, v104
	v_cvt_pk_bf16_f32 v0, v0, v17
	v_add3_u32 v18, 0, v18, v19
	ds_write_b16 v18, v0 offset:17408
	v_cvt_pk_bf16_f32 v0, v1, v17
	ds_write_b16 v18, v0 offset:17544
	v_cvt_pk_bf16_f32 v0, v2, v17
	ds_write_b16 v18, v0 offset:17680
	v_cvt_pk_bf16_f32 v0, v3, v17
	ds_write_b16 v18, v0 offset:17816
	v_cvt_pk_bf16_f32 v0, v4, v17
	ds_write_b16 v18, v0 offset:17952
	v_cvt_pk_bf16_f32 v0, v5, v17
	ds_write_b16 v18, v0 offset:18088
	v_cvt_pk_bf16_f32 v0, v6, v17
	ds_write_b16 v18, v0 offset:18224
	v_cvt_pk_bf16_f32 v0, v7, v17
	ds_write_b16 v18, v0 offset:18360
	v_cvt_pk_bf16_f32 v0, v8, v17
	ds_write_b16 v18, v0 offset:18496
	v_cvt_pk_bf16_f32 v0, v9, v17
	ds_write_b16 v18, v0 offset:18632
	v_cvt_pk_bf16_f32 v0, v10, v17
	ds_write_b16 v18, v0 offset:18768
	v_cvt_pk_bf16_f32 v0, v11, v17
	ds_write_b16 v18, v0 offset:18904
	v_cvt_pk_bf16_f32 v0, v12, v17
	ds_write_b16 v18, v0 offset:19040
	v_cvt_pk_bf16_f32 v0, v13, v17
	s_movk_i32 s2, 0x100
	ds_write_b16 v18, v0 offset:19176
	v_cvt_pk_bf16_f32 v0, v14, v17
	v_cmp_gt_i32_e32 vcc, s2, v106
	ds_write_b16 v18, v0 offset:19312
	v_cvt_pk_bf16_f32 v0, v15, v17
	ds_write_b16 v18, v0 offset:19448
	s_and_saveexec_b64 s[38:39], vcc
	s_cbranch_execz .LBB0_759
	v_add_u32_e32 v218, 0x8800, v44
	v_mov_b32_e32 v219, 0x18c00
	ds_read_b32 v212, v218 offset:0
	s_waitcnt lgkmcnt(0)
	ds_read_b32 v213, v218 offset:1040
	ds_read_b128 v[68:71], v219 offset:256
	v_add_f32_e32 v138, 0, v212
	ds_write_b32 v218, v138 offset:0
	s_waitcnt lgkmcnt(0)
	ds_read_b32 v212, v218 offset:2080
	ds_read_b128 v[0:3], v219 offset:512
	v_fma_f32 v214, -v138, v68, v213
	v_mov_b32_e32 v215, 0
	v_mov_b32_e32 v216, 0
	v_mov_b32_e32 v217, 0
	v_add_f32_e32 v214, v215, v214
	v_add_f32_e32 v215, v216, v217
	v_add_f32_e32 v139, v215, v214
	ds_write_b32 v218, v139 offset:1040
	s_waitcnt lgkmcnt(0)
	ds_read_b32 v213, v218 offset:3120
	ds_read_b128 v[68:71], v219 offset:768
	v_fma_f32 v214, -v138, v0, v212
	v_fma_f32 v215, -v139, v1, 0
	v_mov_b32_e32 v216, 0
	v_mov_b32_e32 v217, 0
	v_add_f32_e32 v214, v215, v214
	v_add_f32_e32 v215, v216, v217
	v_add_f32_e32 v140, v215, v214
	ds_write_b32 v218, v140 offset:2080
	s_waitcnt lgkmcnt(0)
	ds_read_b32 v212, v218 offset:4160
	ds_read_b128 v[0:3], v219 offset:1024
	v_fma_f32 v214, -v138, v68, v213
	v_fma_f32 v215, -v139, v69, 0
	v_fma_f32 v216, -v140, v70, 0
	v_mov_b32_e32 v217, 0
	v_add_f32_e32 v214, v215, v214
	v_add_f32_e32 v215, v216, v217
	v_add_f32_e32 v141, v215, v214
	ds_write_b32 v218, v141 offset:3120
	s_waitcnt lgkmcnt(0)
	ds_read_b32 v213, v218 offset:5200
	ds_read_b128 v[68:71], v219 offset:1280
	ds_read_b128 v[72:75], v219 offset:1296
	v_fma_f32 v214, -v138, v0, v212
	v_fma_f32 v215, -v139, v1, 0
	v_fma_f32 v216, -v140, v2, 0
	v_fma_f32 v217, -v141, v3, 0
	v_add_f32_e32 v214, v215, v214
	v_add_f32_e32 v215, v216, v217
	v_add_f32_e32 v142, v215, v214
	ds_write_b32 v218, v142 offset:4160
	s_waitcnt lgkmcnt(0)
	ds_read_b32 v212, v218 offset:6240
	ds_read_b128 v[0:3], v219 offset:1536
	ds_read_b128 v[4:7], v219 offset:1552
	v_fma_f32 v214, -v138, v68, v213
	v_fma_f32 v215, -v139, v69, 0
	v_fma_f32 v216, -v140, v70, 0
	v_fma_f32 v217, -v141, v71, 0
	v_fma_f32 v214, -v142, v72, v214
	v_add_f32_e32 v214, v215, v214
	v_add_f32_e32 v215, v216, v217
	v_add_f32_e32 v143, v215, v214
	ds_write_b32 v218, v143 offset:5200
	s_waitcnt lgkmcnt(0)
	ds_read_b32 v213, v218 offset:7280
	ds_read_b128 v[68:71], v219 offset:1792
	ds_read_b128 v[72:75], v219 offset:1808
	v_fma_f32 v214, -v138, v0, v212
	v_fma_f32 v215, -v139, v1, 0
	v_fma_f32 v216, -v140, v2, 0
	v_fma_f32 v217, -v141, v3, 0
	v_fma_f32 v214, -v142, v4, v214
	v_fma_f32 v215, -v143, v5, v215
	v_add_f32_e32 v214, v215, v214
	v_add_f32_e32 v215, v216, v217
	v_add_f32_e32 v144, v215, v214
	ds_write_b32 v218, v144 offset:6240
	s_waitcnt lgkmcnt(0)
	ds_read_b32 v212, v218 offset:8320
	ds_read_b128 v[0:3], v219 offset:2048
	ds_read_b128 v[4:7], v219 offset:2064
	v_fma_f32 v214, -v138, v68, v213
	v_fma_f32 v215, -v139, v69, 0
	v_fma_f32 v216, -v140, v70, 0
	v_fma_f32 v217, -v141, v71, 0
	v_fma_f32 v214, -v142, v72, v214
	v_fma_f32 v215, -v143, v73, v215
	v_fma_f32 v216, -v144, v74, v216
	v_add_f32_e32 v214, v215, v214
	v_add_f32_e32 v215, v216, v217
	v_add_f32_e32 v145, v215, v214
	ds_write_b32 v218, v145 offset:7280
	s_waitcnt lgkmcnt(0)
	ds_read_b32 v213, v218 offset:9360
	ds_read_b128 v[68:71], v219 offset:2304
	ds_read_b128 v[72:75], v219 offset:2320
	ds_read_b128 v[76:79], v219 offset:2336
	v_fma_f32 v214, -v138, v0, v212
	v_fma_f32 v215, -v139, v1, 0
	v_fma_f32 v216, -v140, v2, 0
	v_fma_f32 v217, -v141, v3, 0
	v_fma_f32 v214, -v142, v4, v214
	v_fma_f32 v215, -v143, v5, v215
	v_fma_f32 v216, -v144, v6, v216
	v_fma_f32 v217, -v145, v7, v217
	v_add_f32_e32 v214, v215, v214
	v_add_f32_e32 v215, v216, v217
	v_add_f32_e32 v146, v215, v214
	ds_write_b32 v218, v146 offset:8320
	s_waitcnt lgkmcnt(0)
	ds_read_b32 v212, v218 offset:10400
	ds_read_b128 v[0:3], v219 offset:2560
	ds_read_b128 v[4:7], v219 offset:2576
	ds_read_b128 v[8:11], v219 offset:2592
	v_fma_f32 v214, -v138, v68, v213
	v_fma_f32 v215, -v139, v69, 0
	v_fma_f32 v216, -v140, v70, 0
	v_fma_f32 v217, -v141, v71, 0
	v_fma_f32 v214, -v142, v72, v214
	v_fma_f32 v215, -v143, v73, v215
	v_fma_f32 v216, -v144, v74, v216
	v_fma_f32 v217, -v145, v75, v217
	v_fma_f32 v214, -v146, v76, v214
	v_add_f32_e32 v214, v215, v214
	v_add_f32_e32 v215, v216, v217
	v_add_f32_e32 v147, v215, v214
	ds_write_b32 v218, v147 offset:9360
	s_waitcnt lgkmcnt(0)
	ds_read_b32 v213, v218 offset:11440
	ds_read_b128 v[68:71], v219 offset:2816
	ds_read_b128 v[72:75], v219 offset:2832
	ds_read_b128 v[76:79], v219 offset:2848
	v_fma_f32 v214, -v138, v0, v212
	v_fma_f32 v215, -v139, v1, 0
	v_fma_f32 v216, -v140, v2, 0
	v_fma_f32 v217, -v141, v3, 0
	v_fma_f32 v214, -v142, v4, v214
	v_fma_f32 v215, -v143, v5, v215
	v_fma_f32 v216, -v144, v6, v216
	v_fma_f32 v217, -v145, v7, v217
	v_fma_f32 v214, -v146, v8, v214
	v_fma_f32 v215, -v147, v9, v215
	v_add_f32_e32 v214, v215, v214
	v_add_f32_e32 v215, v216, v217
	v_add_f32_e32 v148, v215, v214
	ds_write_b32 v218, v148 offset:10400
	s_waitcnt lgkmcnt(0)
	ds_read_b32 v212, v218 offset:12480
	ds_read_b128 v[0:3], v219 offset:3072
	ds_read_b128 v[4:7], v219 offset:3088
	ds_read_b128 v[8:11], v219 offset:3104
	v_fma_f32 v214, -v138, v68, v213
	v_fma_f32 v215, -v139, v69, 0
	v_fma_f32 v216, -v140, v70, 0
	v_fma_f32 v217, -v141, v71, 0
	v_fma_f32 v214, -v142, v72, v214
	v_fma_f32 v215, -v143, v73, v215
	v_fma_f32 v216, -v144, v74, v216
	v_fma_f32 v217, -v145, v75, v217
	v_fma_f32 v214, -v146, v76, v214
	v_fma_f32 v215, -v147, v77, v215
	v_fma_f32 v216, -v148, v78, v216
	v_add_f32_e32 v214, v215, v214
	v_add_f32_e32 v215, v216, v217
	v_add_f32_e32 v149, v215, v214
	ds_write_b32 v218, v149 offset:11440
	s_waitcnt lgkmcnt(0)
	ds_read_b32 v213, v218 offset:13520
	ds_read_b128 v[68:71], v219 offset:3328
	ds_read_b128 v[72:75], v219 offset:3344
	ds_read_b128 v[76:79], v219 offset:3360
	ds_read_b128 v[80:83], v219 offset:3376
	v_fma_f32 v214, -v138, v0, v212
	v_fma_f32 v215, -v139, v1, 0
	v_fma_f32 v216, -v140, v2, 0
	v_fma_f32 v217, -v141, v3, 0
	v_fma_f32 v214, -v142, v4, v214
	v_fma_f32 v215, -v143, v5, v215
	v_fma_f32 v216, -v144, v6, v216
	v_fma_f32 v217, -v145, v7, v217
	v_fma_f32 v214, -v146, v8, v214
	v_fma_f32 v215, -v147, v9, v215
	v_fma_f32 v216, -v148, v10, v216
	v_fma_f32 v217, -v149, v11, v217
	v_add_f32_e32 v214, v215, v214
	v_add_f32_e32 v215, v216, v217
	v_add_f32_e32 v150, v215, v214
	ds_write_b32 v218, v150 offset:12480
	s_waitcnt lgkmcnt(0)
	ds_read_b32 v212, v218 offset:14560
	ds_read_b128 v[0:3], v219 offset:3584
	ds_read_b128 v[4:7], v219 offset:3600
	ds_read_b128 v[8:11], v219 offset:3616
	ds_read_b128 v[12:15], v219 offset:3632
	v_fma_f32 v214, -v138, v68, v213
	v_fma_f32 v215, -v139, v69, 0
	v_fma_f32 v216, -v140, v70, 0
	v_fma_f32 v217, -v141, v71, 0
	v_fma_f32 v214, -v142, v72, v214
	v_fma_f32 v215, -v143, v73, v215
	v_fma_f32 v216, -v144, v74, v216
	v_fma_f32 v217, -v145, v75, v217
	v_fma_f32 v214, -v146, v76, v214
	v_fma_f32 v215, -v147, v77, v215
	v_fma_f32 v216, -v148, v78, v216
	v_fma_f32 v217, -v149, v79, v217
	v_fma_f32 v214, -v150, v80, v214
	v_add_f32_e32 v214, v215, v214
	v_add_f32_e32 v215, v216, v217
	v_add_f32_e32 v151, v215, v214
	ds_write_b32 v218, v151 offset:13520
	s_waitcnt lgkmcnt(0)
	ds_read_b32 v213, v218 offset:15600
	ds_read_b128 v[68:71], v219 offset:3840
	ds_read_b128 v[72:75], v219 offset:3856
	ds_read_b128 v[76:79], v219 offset:3872
	ds_read_b128 v[80:83], v219 offset:3888
	v_fma_f32 v214, -v138, v0, v212
	v_fma_f32 v215, -v139, v1, 0
	v_fma_f32 v216, -v140, v2, 0
	v_fma_f32 v217, -v141, v3, 0
	v_fma_f32 v214, -v142, v4, v214
	v_fma_f32 v215, -v143, v5, v215
	v_fma_f32 v216, -v144, v6, v216
	v_fma_f32 v217, -v145, v7, v217
	v_fma_f32 v214, -v146, v8, v214
	v_fma_f32 v215, -v147, v9, v215
	v_fma_f32 v216, -v148, v10, v216
	v_fma_f32 v217, -v149, v11, v217
	v_fma_f32 v214, -v150, v12, v214
	v_fma_f32 v215, -v151, v13, v215
	v_add_f32_e32 v214, v215, v214
	v_add_f32_e32 v215, v216, v217
	v_add_f32_e32 v152, v215, v214
	ds_write_b32 v218, v152 offset:14560
	s_waitcnt lgkmcnt(0)
	ds_read_b32 v212, v218 offset:16640
	ds_read_b128 v[0:3], v219 offset:4096
	ds_read_b128 v[4:7], v219 offset:4112
	ds_read_b128 v[8:11], v219 offset:4128
	ds_read_b128 v[12:15], v219 offset:4144
	v_fma_f32 v214, -v138, v68, v213
	v_fma_f32 v215, -v139, v69, 0
	v_fma_f32 v216, -v140, v70, 0
	v_fma_f32 v217, -v141, v71, 0
	v_fma_f32 v214, -v142, v72, v214
	v_fma_f32 v215, -v143, v73, v215
	v_fma_f32 v216, -v144, v74, v216
	v_fma_f32 v217, -v145, v75, v217
	v_fma_f32 v214, -v146, v76, v214
	v_fma_f32 v215, -v147, v77, v215
	v_fma_f32 v216, -v148, v78, v216
	v_fma_f32 v217, -v149, v79, v217
	v_fma_f32 v214, -v150, v80, v214
	v_fma_f32 v215, -v151, v81, v215
	v_fma_f32 v216, -v152, v82, v216
	v_add_f32_e32 v214, v215, v214
	v_add_f32_e32 v215, v216, v217
	v_add_f32_e32 v153, v215, v214
	ds_write_b32 v218, v153 offset:15600
	s_waitcnt lgkmcnt(0)
	ds_read_b32 v213, v218 offset:17680
	ds_read_b128 v[68:71], v219 offset:4352
	ds_read_b128 v[72:75], v219 offset:4368
	ds_read_b128 v[76:79], v219 offset:4384
	ds_read_b128 v[80:83], v219 offset:4400
	ds_read_b128 v[84:87], v219 offset:4416
	v_fma_f32 v214, -v138, v0, v212
	v_fma_f32 v215, -v139, v1, 0
	v_fma_f32 v216, -v140, v2, 0
	v_fma_f32 v217, -v141, v3, 0
	v_fma_f32 v214, -v142, v4, v214
	v_fma_f32 v215, -v143, v5, v215
	v_fma_f32 v216, -v144, v6, v216
	v_fma_f32 v217, -v145, v7, v217
	v_fma_f32 v214, -v146, v8, v214
	v_fma_f32 v215, -v147, v9, v215
	v_fma_f32 v216, -v148, v10, v216
	v_fma_f32 v217, -v149, v11, v217
	v_fma_f32 v214, -v150, v12, v214
	v_fma_f32 v215, -v151, v13, v215
	v_fma_f32 v216, -v152, v14, v216
	v_fma_f32 v217, -v153, v15, v217
	v_add_f32_e32 v214, v215, v214
	v_add_f32_e32 v215, v216, v217
	v_add_f32_e32 v154, v215, v214
	ds_write_b32 v218, v154 offset:16640
	s_waitcnt lgkmcnt(0)
	ds_read_b32 v212, v218 offset:18720
	ds_read_b128 v[0:3], v219 offset:4608
	ds_read_b128 v[4:7], v219 offset:4624
	ds_read_b128 v[8:11], v219 offset:4640
	ds_read_b128 v[12:15], v219 offset:4656
	ds_read_b128 v[18:21], v219 offset:4672
	v_fma_f32 v214, -v138, v68, v213
	v_fma_f32 v215, -v139, v69, 0
	v_fma_f32 v216, -v140, v70, 0
	v_fma_f32 v217, -v141, v71, 0
	v_fma_f32 v214, -v142, v72, v214
	v_fma_f32 v215, -v143, v73, v215
	v_fma_f32 v216, -v144, v74, v216
	v_fma_f32 v217, -v145, v75, v217
	v_fma_f32 v214, -v146, v76, v214
	v_fma_f32 v215, -v147, v77, v215
	v_fma_f32 v216, -v148, v78, v216
	v_fma_f32 v217, -v149, v79, v217
	v_fma_f32 v214, -v150, v80, v214
	v_fma_f32 v215, -v151, v81, v215
	v_fma_f32 v216, -v152, v82, v216
	v_fma_f32 v217, -v153, v83, v217
	v_fma_f32 v214, -v154, v84, v214
	v_add_f32_e32 v214, v215, v214
	v_add_f32_e32 v215, v216, v217
	v_add_f32_e32 v155, v215, v214
	ds_write_b32 v218, v155 offset:17680
	s_waitcnt lgkmcnt(0)
	ds_read_b32 v213, v218 offset:19760
	ds_read_b128 v[68:71], v219 offset:4864
	ds_read_b128 v[72:75], v219 offset:4880
	ds_read_b128 v[76:79], v219 offset:4896
	ds_read_b128 v[80:83], v219 offset:4912
	ds_read_b128 v[84:87], v219 offset:4928
	v_fma_f32 v214, -v138, v0, v212
	v_fma_f32 v215, -v139, v1, 0
	v_fma_f32 v216, -v140, v2, 0
	v_fma_f32 v217, -v141, v3, 0
	v_fma_f32 v214, -v142, v4, v214
	v_fma_f32 v215, -v143, v5, v215
	v_fma_f32 v216, -v144, v6, v216
	v_fma_f32 v217, -v145, v7, v217
	v_fma_f32 v214, -v146, v8, v214
	v_fma_f32 v215, -v147, v9, v215
	v_fma_f32 v216, -v148, v10, v216
	v_fma_f32 v217, -v149, v11, v217
	v_fma_f32 v214, -v150, v12, v214
	v_fma_f32 v215, -v151, v13, v215
	v_fma_f32 v216, -v152, v14, v216
	v_fma_f32 v217, -v153, v15, v217
	v_fma_f32 v214, -v154, v18, v214
	v_fma_f32 v215, -v155, v19, v215
	v_add_f32_e32 v214, v215, v214
	v_add_f32_e32 v215, v216, v217
	v_add_f32_e32 v156, v215, v214
	ds_write_b32 v218, v156 offset:18720
	s_waitcnt lgkmcnt(0)
	ds_read_b32 v212, v218 offset:20800
	ds_read_b128 v[0:3], v219 offset:5120
	ds_read_b128 v[4:7], v219 offset:5136
	ds_read_b128 v[8:11], v219 offset:5152
	ds_read_b128 v[12:15], v219 offset:5168
	ds_read_b128 v[18:21], v219 offset:5184
	v_fma_f32 v214, -v138, v68, v213
	v_fma_f32 v215, -v139, v69, 0
	v_fma_f32 v216, -v140, v70, 0
	v_fma_f32 v217, -v141, v71, 0
	v_fma_f32 v214, -v142, v72, v214
	v_fma_f32 v215, -v143, v73, v215
	v_fma_f32 v216, -v144, v74, v216
	v_fma_f32 v217, -v145, v75, v217
	v_fma_f32 v214, -v146, v76, v214
	v_fma_f32 v215, -v147, v77, v215
	v_fma_f32 v216, -v148, v78, v216
	v_fma_f32 v217, -v149, v79, v217
	v_fma_f32 v214, -v150, v80, v214
	v_fma_f32 v215, -v151, v81, v215
	v_fma_f32 v216, -v152, v82, v216
	v_fma_f32 v217, -v153, v83, v217
	v_fma_f32 v214, -v154, v84, v214
	v_fma_f32 v215, -v155, v85, v215
	v_fma_f32 v216, -v156, v86, v216
	v_add_f32_e32 v214, v215, v214
	v_add_f32_e32 v215, v216, v217
	v_add_f32_e32 v157, v215, v214
	ds_write_b32 v218, v157 offset:19760
	s_waitcnt lgkmcnt(0)
	ds_read_b32 v213, v218 offset:21840
	ds_read_b128 v[68:71], v219 offset:5376
	ds_read_b128 v[72:75], v219 offset:5392
	ds_read_b128 v[76:79], v219 offset:5408
	ds_read_b128 v[80:83], v219 offset:5424
	ds_read_b128 v[84:87], v219 offset:5440
	ds_read_b128 v[88:91], v219 offset:5456
	v_fma_f32 v214, -v138, v0, v212
	v_fma_f32 v215, -v139, v1, 0
	v_fma_f32 v216, -v140, v2, 0
	v_fma_f32 v217, -v141, v3, 0
	v_fma_f32 v214, -v142, v4, v214
	v_fma_f32 v215, -v143, v5, v215
	v_fma_f32 v216, -v144, v6, v216
	v_fma_f32 v217, -v145, v7, v217
	v_fma_f32 v214, -v146, v8, v214
	v_fma_f32 v215, -v147, v9, v215
	v_fma_f32 v216, -v148, v10, v216
	v_fma_f32 v217, -v149, v11, v217
	v_fma_f32 v214, -v150, v12, v214
	v_fma_f32 v215, -v151, v13, v215
	v_fma_f32 v216, -v152, v14, v216
	v_fma_f32 v217, -v153, v15, v217
	v_fma_f32 v214, -v154, v18, v214
	v_fma_f32 v215, -v155, v19, v215
	v_fma_f32 v216, -v156, v20, v216
	v_fma_f32 v217, -v157, v21, v217
	v_add_f32_e32 v214, v215, v214
	v_add_f32_e32 v215, v216, v217
	v_add_f32_e32 v158, v215, v214
	ds_write_b32 v218, v158 offset:20800
	s_waitcnt lgkmcnt(0)
	ds_read_b32 v212, v218 offset:22880
	ds_read_b128 v[0:3], v219 offset:5632
	ds_read_b128 v[4:7], v219 offset:5648
	ds_read_b128 v[8:11], v219 offset:5664
	ds_read_b128 v[12:15], v219 offset:5680
	ds_read_b128 v[18:21], v219 offset:5696
	ds_read_b128 v[22:25], v219 offset:5712
	v_fma_f32 v214, -v138, v68, v213
	v_fma_f32 v215, -v139, v69, 0
	v_fma_f32 v216, -v140, v70, 0
	v_fma_f32 v217, -v141, v71, 0
	v_fma_f32 v214, -v142, v72, v214
	v_fma_f32 v215, -v143, v73, v215
	v_fma_f32 v216, -v144, v74, v216
	v_fma_f32 v217, -v145, v75, v217
	v_fma_f32 v214, -v146, v76, v214
	v_fma_f32 v215, -v147, v77, v215
	v_fma_f32 v216, -v148, v78, v216
	v_fma_f32 v217, -v149, v79, v217
	v_fma_f32 v214, -v150, v80, v214
	v_fma_f32 v215, -v151, v81, v215
	v_fma_f32 v216, -v152, v82, v216
	v_fma_f32 v217, -v153, v83, v217
	v_fma_f32 v214, -v154, v84, v214
	v_fma_f32 v215, -v155, v85, v215
	v_fma_f32 v216, -v156, v86, v216
	v_fma_f32 v217, -v157, v87, v217
	v_fma_f32 v214, -v158, v88, v214
	v_add_f32_e32 v214, v215, v214
	v_add_f32_e32 v215, v216, v217
	v_add_f32_e32 v159, v215, v214
	ds_write_b32 v218, v159 offset:21840
	s_waitcnt lgkmcnt(0)
	ds_read_b32 v213, v218 offset:23920
	ds_read_b128 v[68:71], v219 offset:5888
	ds_read_b128 v[72:75], v219 offset:5904
	ds_read_b128 v[76:79], v219 offset:5920
	ds_read_b128 v[80:83], v219 offset:5936
	ds_read_b128 v[84:87], v219 offset:5952
	ds_read_b128 v[88:91], v219 offset:5968
	v_fma_f32 v214, -v138, v0, v212
	v_fma_f32 v215, -v139, v1, 0
	v_fma_f32 v216, -v140, v2, 0
	v_fma_f32 v217, -v141, v3, 0
	v_fma_f32 v214, -v142, v4, v214
	v_fma_f32 v215, -v143, v5, v215
	v_fma_f32 v216, -v144, v6, v216
	v_fma_f32 v217, -v145, v7, v217
	v_fma_f32 v214, -v146, v8, v214
	v_fma_f32 v215, -v147, v9, v215
	v_fma_f32 v216, -v148, v10, v216
	v_fma_f32 v217, -v149, v11, v217
	v_fma_f32 v214, -v150, v12, v214
	v_fma_f32 v215, -v151, v13, v215
	v_fma_f32 v216, -v152, v14, v216
	v_fma_f32 v217, -v153, v15, v217
	v_fma_f32 v214, -v154, v18, v214
	v_fma_f32 v215, -v155, v19, v215
	v_fma_f32 v216, -v156, v20, v216
	v_fma_f32 v217, -v157, v21, v217
	v_fma_f32 v214, -v158, v22, v214
	v_fma_f32 v215, -v159, v23, v215
	v_add_f32_e32 v214, v215, v214
	v_add_f32_e32 v215, v216, v217
	v_add_f32_e32 v160, v215, v214
	ds_write_b32 v218, v160 offset:22880
	s_waitcnt lgkmcnt(0)
	ds_read_b32 v212, v218 offset:24960
	ds_read_b128 v[0:3], v219 offset:6144
	ds_read_b128 v[4:7], v219 offset:6160
	ds_read_b128 v[8:11], v219 offset:6176
	ds_read_b128 v[12:15], v219 offset:6192
	ds_read_b128 v[18:21], v219 offset:6208
	ds_read_b128 v[22:25], v219 offset:6224
	v_fma_f32 v214, -v138, v68, v213
	v_fma_f32 v215, -v139, v69, 0
	v_fma_f32 v216, -v140, v70, 0
	v_fma_f32 v217, -v141, v71, 0
	v_fma_f32 v214, -v142, v72, v214
	v_fma_f32 v215, -v143, v73, v215
	v_fma_f32 v216, -v144, v74, v216
	v_fma_f32 v217, -v145, v75, v217
	v_fma_f32 v214, -v146, v76, v214
	v_fma_f32 v215, -v147, v77, v215
	v_fma_f32 v216, -v148, v78, v216
	v_fma_f32 v217, -v149, v79, v217
	v_fma_f32 v214, -v150, v80, v214
	v_fma_f32 v215, -v151, v81, v215
	v_fma_f32 v216, -v152, v82, v216
	v_fma_f32 v217, -v153, v83, v217
	v_fma_f32 v214, -v154, v84, v214
	v_fma_f32 v215, -v155, v85, v215
	v_fma_f32 v216, -v156, v86, v216
	v_fma_f32 v217, -v157, v87, v217
	v_fma_f32 v214, -v158, v88, v214
	v_fma_f32 v215, -v159, v89, v215
	v_fma_f32 v216, -v160, v90, v216
	v_add_f32_e32 v214, v215, v214
	v_add_f32_e32 v215, v216, v217
	v_add_f32_e32 v161, v215, v214
	ds_write_b32 v218, v161 offset:23920
	s_waitcnt lgkmcnt(0)
	ds_read_b32 v213, v218 offset:26000
	ds_read_b128 v[68:71], v219 offset:6400
	ds_read_b128 v[72:75], v219 offset:6416
	ds_read_b128 v[76:79], v219 offset:6432
	ds_read_b128 v[80:83], v219 offset:6448
	ds_read_b128 v[84:87], v219 offset:6464
	ds_read_b128 v[88:91], v219 offset:6480
	ds_read_b128 v[92:95], v219 offset:6496
	v_fma_f32 v214, -v138, v0, v212
	v_fma_f32 v215, -v139, v1, 0
	v_fma_f32 v216, -v140, v2, 0
	v_fma_f32 v217, -v141, v3, 0
	v_fma_f32 v214, -v142, v4, v214
	v_fma_f32 v215, -v143, v5, v215
	v_fma_f32 v216, -v144, v6, v216
	v_fma_f32 v217, -v145, v7, v217
	v_fma_f32 v214, -v146, v8, v214
	v_fma_f32 v215, -v147, v9, v215
	v_fma_f32 v216, -v148, v10, v216
	v_fma_f32 v217, -v149, v11, v217
	v_fma_f32 v214, -v150, v12, v214
	v_fma_f32 v215, -v151, v13, v215
	v_fma_f32 v216, -v152, v14, v216
	v_fma_f32 v217, -v153, v15, v217
	v_fma_f32 v214, -v154, v18, v214
	v_fma_f32 v215, -v155, v19, v215
	v_fma_f32 v216, -v156, v20, v216
	v_fma_f32 v217, -v157, v21, v217
	v_fma_f32 v214, -v158, v22, v214
	v_fma_f32 v215, -v159, v23, v215
	v_fma_f32 v216, -v160, v24, v216
	v_fma_f32 v217, -v161, v25, v217
	v_add_f32_e32 v214, v215, v214
	v_add_f32_e32 v215, v216, v217
	v_add_f32_e32 v162, v215, v214
	ds_write_b32 v218, v162 offset:24960
	s_waitcnt lgkmcnt(0)
	ds_read_b32 v212, v218 offset:27040
	ds_read_b128 v[0:3], v219 offset:6656
	ds_read_b128 v[4:7], v219 offset:6672
	ds_read_b128 v[8:11], v219 offset:6688
	ds_read_b128 v[12:15], v219 offset:6704
	ds_read_b128 v[18:21], v219 offset:6720
	ds_read_b128 v[22:25], v219 offset:6736
	ds_read_b128 v[26:29], v219 offset:6752
	v_fma_f32 v214, -v138, v68, v213
	v_fma_f32 v215, -v139, v69, 0
	v_fma_f32 v216, -v140, v70, 0
	v_fma_f32 v217, -v141, v71, 0
	v_fma_f32 v214, -v142, v72, v214
	v_fma_f32 v215, -v143, v73, v215
	v_fma_f32 v216, -v144, v74, v216
	v_fma_f32 v217, -v145, v75, v217
	v_fma_f32 v214, -v146, v76, v214
	v_fma_f32 v215, -v147, v77, v215
	v_fma_f32 v216, -v148, v78, v216
	v_fma_f32 v217, -v149, v79, v217
	v_fma_f32 v214, -v150, v80, v214
	v_fma_f32 v215, -v151, v81, v215
	v_fma_f32 v216, -v152, v82, v216
	v_fma_f32 v217, -v153, v83, v217
	v_fma_f32 v214, -v154, v84, v214
	v_fma_f32 v215, -v155, v85, v215
	v_fma_f32 v216, -v156, v86, v216
	v_fma_f32 v217, -v157, v87, v217
	v_fma_f32 v214, -v158, v88, v214
	v_fma_f32 v215, -v159, v89, v215
	v_fma_f32 v216, -v160, v90, v216
	v_fma_f32 v217, -v161, v91, v217
	v_fma_f32 v214, -v162, v92, v214
	v_add_f32_e32 v214, v215, v214
	v_add_f32_e32 v215, v216, v217
	v_add_f32_e32 v163, v215, v214
	ds_write_b32 v218, v163 offset:26000
	s_waitcnt lgkmcnt(0)
	ds_read_b32 v213, v218 offset:28080
	ds_read_b128 v[68:71], v219 offset:6912
	ds_read_b128 v[72:75], v219 offset:6928
	ds_read_b128 v[76:79], v219 offset:6944
	ds_read_b128 v[80:83], v219 offset:6960
	ds_read_b128 v[84:87], v219 offset:6976
	ds_read_b128 v[88:91], v219 offset:6992
	ds_read_b128 v[92:95], v219 offset:7008
	v_fma_f32 v214, -v138, v0, v212
	v_fma_f32 v215, -v139, v1, 0
	v_fma_f32 v216, -v140, v2, 0
	v_fma_f32 v217, -v141, v3, 0
	v_fma_f32 v214, -v142, v4, v214
	v_fma_f32 v215, -v143, v5, v215
	v_fma_f32 v216, -v144, v6, v216
	v_fma_f32 v217, -v145, v7, v217
	v_fma_f32 v214, -v146, v8, v214
	v_fma_f32 v215, -v147, v9, v215
	v_fma_f32 v216, -v148, v10, v216
	v_fma_f32 v217, -v149, v11, v217
	v_fma_f32 v214, -v150, v12, v214
	v_fma_f32 v215, -v151, v13, v215
	v_fma_f32 v216, -v152, v14, v216
	v_fma_f32 v217, -v153, v15, v217
	v_fma_f32 v214, -v154, v18, v214
	v_fma_f32 v215, -v155, v19, v215
	v_fma_f32 v216, -v156, v20, v216
	v_fma_f32 v217, -v157, v21, v217
	v_fma_f32 v214, -v158, v22, v214
	v_fma_f32 v215, -v159, v23, v215
	v_fma_f32 v216, -v160, v24, v216
	v_fma_f32 v217, -v161, v25, v217
	v_fma_f32 v214, -v162, v26, v214
	v_fma_f32 v215, -v163, v27, v215
	v_add_f32_e32 v214, v215, v214
	v_add_f32_e32 v215, v216, v217
	v_add_f32_e32 v164, v215, v214
	ds_write_b32 v218, v164 offset:27040
	s_waitcnt lgkmcnt(0)
	ds_read_b32 v212, v218 offset:29120
	ds_read_b128 v[0:3], v219 offset:7168
	ds_read_b128 v[4:7], v219 offset:7184
	ds_read_b128 v[8:11], v219 offset:7200
	ds_read_b128 v[12:15], v219 offset:7216
	ds_read_b128 v[18:21], v219 offset:7232
	ds_read_b128 v[22:25], v219 offset:7248
	ds_read_b128 v[26:29], v219 offset:7264
	v_fma_f32 v214, -v138, v68, v213
	v_fma_f32 v215, -v139, v69, 0
	v_fma_f32 v216, -v140, v70, 0
	v_fma_f32 v217, -v141, v71, 0
	v_fma_f32 v214, -v142, v72, v214
	v_fma_f32 v215, -v143, v73, v215
	v_fma_f32 v216, -v144, v74, v216
	v_fma_f32 v217, -v145, v75, v217
	v_fma_f32 v214, -v146, v76, v214
	v_fma_f32 v215, -v147, v77, v215
	v_fma_f32 v216, -v148, v78, v216
	v_fma_f32 v217, -v149, v79, v217
	v_fma_f32 v214, -v150, v80, v214
	v_fma_f32 v215, -v151, v81, v215
	v_fma_f32 v216, -v152, v82, v216
	v_fma_f32 v217, -v153, v83, v217
	v_fma_f32 v214, -v154, v84, v214
	v_fma_f32 v215, -v155, v85, v215
	v_fma_f32 v216, -v156, v86, v216
	v_fma_f32 v217, -v157, v87, v217
	v_fma_f32 v214, -v158, v88, v214
	v_fma_f32 v215, -v159, v89, v215
	v_fma_f32 v216, -v160, v90, v216
	v_fma_f32 v217, -v161, v91, v217
	v_fma_f32 v214, -v162, v92, v214
	v_fma_f32 v215, -v163, v93, v215
	v_fma_f32 v216, -v164, v94, v216
	v_add_f32_e32 v214, v215, v214
	v_add_f32_e32 v215, v216, v217
	v_add_f32_e32 v165, v215, v214
	ds_write_b32 v218, v165 offset:28080
	s_waitcnt lgkmcnt(0)
	ds_read_b32 v213, v218 offset:30160
	ds_read_b128 v[68:71], v219 offset:7424
	ds_read_b128 v[72:75], v219 offset:7440
	ds_read_b128 v[76:79], v219 offset:7456
	ds_read_b128 v[80:83], v219 offset:7472
	ds_read_b128 v[84:87], v219 offset:7488
	ds_read_b128 v[88:91], v219 offset:7504
	ds_read_b128 v[92:95], v219 offset:7520
	ds_read_b128 v[96:99], v219 offset:7536
	v_fma_f32 v214, -v138, v0, v212
	v_fma_f32 v215, -v139, v1, 0
	v_fma_f32 v216, -v140, v2, 0
	v_fma_f32 v217, -v141, v3, 0
	v_fma_f32 v214, -v142, v4, v214
	v_fma_f32 v215, -v143, v5, v215
	v_fma_f32 v216, -v144, v6, v216
	v_fma_f32 v217, -v145, v7, v217
	v_fma_f32 v214, -v146, v8, v214
	v_fma_f32 v215, -v147, v9, v215
	v_fma_f32 v216, -v148, v10, v216
	v_fma_f32 v217, -v149, v11, v217
	v_fma_f32 v214, -v150, v12, v214
	v_fma_f32 v215, -v151, v13, v215
	v_fma_f32 v216, -v152, v14, v216
	v_fma_f32 v217, -v153, v15, v217
	v_fma_f32 v214, -v154, v18, v214
	v_fma_f32 v215, -v155, v19, v215
	v_fma_f32 v216, -v156, v20, v216
	v_fma_f32 v217, -v157, v21, v217
	v_fma_f32 v214, -v158, v22, v214
	v_fma_f32 v215, -v159, v23, v215
	v_fma_f32 v216, -v160, v24, v216
	v_fma_f32 v217, -v161, v25, v217
	v_fma_f32 v214, -v162, v26, v214
	v_fma_f32 v215, -v163, v27, v215
	v_fma_f32 v216, -v164, v28, v216
	v_fma_f32 v217, -v165, v29, v217
	v_add_f32_e32 v214, v215, v214
	v_add_f32_e32 v215, v216, v217
	v_add_f32_e32 v166, v215, v214
	ds_write_b32 v218, v166 offset:29120
	s_waitcnt lgkmcnt(0)
	ds_read_b32 v212, v218 offset:31200
	ds_read_b128 v[0:3], v219 offset:7680
	ds_read_b128 v[4:7], v219 offset:7696
	ds_read_b128 v[8:11], v219 offset:7712
	ds_read_b128 v[12:15], v219 offset:7728
	ds_read_b128 v[18:21], v219 offset:7744
	ds_read_b128 v[22:25], v219 offset:7760
	ds_read_b128 v[26:29], v219 offset:7776
	ds_read_b128 v[30:33], v219 offset:7792
	v_fma_f32 v214, -v138, v68, v213
	v_fma_f32 v215, -v139, v69, 0
	v_fma_f32 v216, -v140, v70, 0
	v_fma_f32 v217, -v141, v71, 0
	v_fma_f32 v214, -v142, v72, v214
	v_fma_f32 v215, -v143, v73, v215
	v_fma_f32 v216, -v144, v74, v216
	v_fma_f32 v217, -v145, v75, v217
	v_fma_f32 v214, -v146, v76, v214
	v_fma_f32 v215, -v147, v77, v215
	v_fma_f32 v216, -v148, v78, v216
	v_fma_f32 v217, -v149, v79, v217
	v_fma_f32 v214, -v150, v80, v214
	v_fma_f32 v215, -v151, v81, v215
	v_fma_f32 v216, -v152, v82, v216
	v_fma_f32 v217, -v153, v83, v217
	v_fma_f32 v214, -v154, v84, v214
	v_fma_f32 v215, -v155, v85, v215
	v_fma_f32 v216, -v156, v86, v216
	v_fma_f32 v217, -v157, v87, v217
	v_fma_f32 v214, -v158, v88, v214
	v_fma_f32 v215, -v159, v89, v215
	v_fma_f32 v216, -v160, v90, v216
	v_fma_f32 v217, -v161, v91, v217
	v_fma_f32 v214, -v162, v92, v214
	v_fma_f32 v215, -v163, v93, v215
	v_fma_f32 v216, -v164, v94, v216
	v_fma_f32 v217, -v165, v95, v217
	v_fma_f32 v214, -v166, v96, v214
	v_add_f32_e32 v214, v215, v214
	v_add_f32_e32 v215, v216, v217
	v_add_f32_e32 v167, v215, v214
	ds_write_b32 v218, v167 offset:30160
	s_waitcnt lgkmcnt(0)
	ds_read_b32 v213, v218 offset:32240
	ds_read_b128 v[68:71], v219 offset:7936
	ds_read_b128 v[72:75], v219 offset:7952
	ds_read_b128 v[76:79], v219 offset:7968
	ds_read_b128 v[80:83], v219 offset:7984
	ds_read_b128 v[84:87], v219 offset:8000
	ds_read_b128 v[88:91], v219 offset:8016
	ds_read_b128 v[92:95], v219 offset:8032
	ds_read_b128 v[96:99], v219 offset:8048
	v_fma_f32 v214, -v138, v0, v212
	v_fma_f32 v215, -v139, v1, 0
	v_fma_f32 v216, -v140, v2, 0
	v_fma_f32 v217, -v141, v3, 0
	v_fma_f32 v214, -v142, v4, v214
	v_fma_f32 v215, -v143, v5, v215
	v_fma_f32 v216, -v144, v6, v216
	v_fma_f32 v217, -v145, v7, v217
	v_fma_f32 v214, -v146, v8, v214
	v_fma_f32 v215, -v147, v9, v215
	v_fma_f32 v216, -v148, v10, v216
	v_fma_f32 v217, -v149, v11, v217
	v_fma_f32 v214, -v150, v12, v214
	v_fma_f32 v215, -v151, v13, v215
	v_fma_f32 v216, -v152, v14, v216
	v_fma_f32 v217, -v153, v15, v217
	v_fma_f32 v214, -v154, v18, v214
	v_fma_f32 v215, -v155, v19, v215
	v_fma_f32 v216, -v156, v20, v216
	v_fma_f32 v217, -v157, v21, v217
	v_fma_f32 v214, -v158, v22, v214
	v_fma_f32 v215, -v159, v23, v215
	v_fma_f32 v216, -v160, v24, v216
	v_fma_f32 v217, -v161, v25, v217
	v_fma_f32 v214, -v162, v26, v214
	v_fma_f32 v215, -v163, v27, v215
	v_fma_f32 v216, -v164, v28, v216
	v_fma_f32 v217, -v165, v29, v217
	v_fma_f32 v214, -v166, v30, v214
	v_fma_f32 v215, -v167, v31, v215
	v_add_f32_e32 v214, v215, v214
	v_add_f32_e32 v215, v216, v217
	v_add_f32_e32 v168, v215, v214
	ds_write_b32 v218, v168 offset:31200
	s_waitcnt lgkmcnt(0)
	ds_read_b32 v212, v218 offset:33280
	ds_read_b128 v[0:3], v219 offset:8192
	ds_read_b128 v[4:7], v219 offset:8208
	ds_read_b128 v[8:11], v219 offset:8224
	ds_read_b128 v[12:15], v219 offset:8240
	ds_read_b128 v[18:21], v219 offset:8256
	ds_read_b128 v[22:25], v219 offset:8272
	ds_read_b128 v[26:29], v219 offset:8288
	ds_read_b128 v[30:33], v219 offset:8304
	v_fma_f32 v214, -v138, v68, v213
	v_fma_f32 v215, -v139, v69, 0
	v_fma_f32 v216, -v140, v70, 0
	v_fma_f32 v217, -v141, v71, 0
	v_fma_f32 v214, -v142, v72, v214
	v_fma_f32 v215, -v143, v73, v215
	v_fma_f32 v216, -v144, v74, v216
	v_fma_f32 v217, -v145, v75, v217
	v_fma_f32 v214, -v146, v76, v214
	v_fma_f32 v215, -v147, v77, v215
	v_fma_f32 v216, -v148, v78, v216
	v_fma_f32 v217, -v149, v79, v217
	v_fma_f32 v214, -v150, v80, v214
	v_fma_f32 v215, -v151, v81, v215
	v_fma_f32 v216, -v152, v82, v216
	v_fma_f32 v217, -v153, v83, v217
	v_fma_f32 v214, -v154, v84, v214
	v_fma_f32 v215, -v155, v85, v215
	v_fma_f32 v216, -v156, v86, v216
	v_fma_f32 v217, -v157, v87, v217
	v_fma_f32 v214, -v158, v88, v214
	v_fma_f32 v215, -v159, v89, v215
	v_fma_f32 v216, -v160, v90, v216
	v_fma_f32 v217, -v161, v91, v217
	v_fma_f32 v214, -v162, v92, v214
	v_fma_f32 v215, -v163, v93, v215
	v_fma_f32 v216, -v164, v94, v216
	v_fma_f32 v217, -v165, v95, v217
	v_fma_f32 v214, -v166, v96, v214
	v_fma_f32 v215, -v167, v97, v215
	v_fma_f32 v216, -v168, v98, v216
	v_add_f32_e32 v214, v215, v214
	v_add_f32_e32 v215, v216, v217
	v_add_f32_e32 v169, v215, v214
	ds_write_b32 v218, v169 offset:32240
	s_waitcnt lgkmcnt(0)
	ds_read_b32 v213, v218 offset:34320
	ds_read_b128 v[68:71], v219 offset:8448
	ds_read_b128 v[72:75], v219 offset:8464
	ds_read_b128 v[76:79], v219 offset:8480
	ds_read_b128 v[80:83], v219 offset:8496
	ds_read_b128 v[84:87], v219 offset:8512
	ds_read_b128 v[88:91], v219 offset:8528
	ds_read_b128 v[92:95], v219 offset:8544
	ds_read_b128 v[96:99], v219 offset:8560
	ds_read_b128 v[100:103], v219 offset:8576
	v_fma_f32 v214, -v138, v0, v212
	v_fma_f32 v215, -v139, v1, 0
	v_fma_f32 v216, -v140, v2, 0
	v_fma_f32 v217, -v141, v3, 0
	v_fma_f32 v214, -v142, v4, v214
	v_fma_f32 v215, -v143, v5, v215
	v_fma_f32 v216, -v144, v6, v216
	v_fma_f32 v217, -v145, v7, v217
	v_fma_f32 v214, -v146, v8, v214
	v_fma_f32 v215, -v147, v9, v215
	v_fma_f32 v216, -v148, v10, v216
	v_fma_f32 v217, -v149, v11, v217
	v_fma_f32 v214, -v150, v12, v214
	v_fma_f32 v215, -v151, v13, v215
	v_fma_f32 v216, -v152, v14, v216
	v_fma_f32 v217, -v153, v15, v217
	v_fma_f32 v214, -v154, v18, v214
	v_fma_f32 v215, -v155, v19, v215
	v_fma_f32 v216, -v156, v20, v216
	v_fma_f32 v217, -v157, v21, v217
	v_fma_f32 v214, -v158, v22, v214
	v_fma_f32 v215, -v159, v23, v215
	v_fma_f32 v216, -v160, v24, v216
	v_fma_f32 v217, -v161, v25, v217
	v_fma_f32 v214, -v162, v26, v214
	v_fma_f32 v215, -v163, v27, v215
	v_fma_f32 v216, -v164, v28, v216
	v_fma_f32 v217, -v165, v29, v217
	v_fma_f32 v214, -v166, v30, v214
	v_fma_f32 v215, -v167, v31, v215
	v_fma_f32 v216, -v168, v32, v216
	v_fma_f32 v217, -v169, v33, v217
	v_add_f32_e32 v214, v215, v214
	v_add_f32_e32 v215, v216, v217
	v_add_f32_e32 v170, v215, v214
	ds_write_b32 v218, v170 offset:33280
	s_waitcnt lgkmcnt(0)
	ds_read_b32 v212, v218 offset:35360
	ds_read_b128 v[0:3], v219 offset:8704
	ds_read_b128 v[4:7], v219 offset:8720
	ds_read_b128 v[8:11], v219 offset:8736
	ds_read_b128 v[12:15], v219 offset:8752
	ds_read_b128 v[18:21], v219 offset:8768
	ds_read_b128 v[22:25], v219 offset:8784
	ds_read_b128 v[26:29], v219 offset:8800
	ds_read_b128 v[30:33], v219 offset:8816
	ds_read_b128 v[34:37], v219 offset:8832
	v_fma_f32 v214, -v138, v68, v213
	v_fma_f32 v215, -v139, v69, 0
	v_fma_f32 v216, -v140, v70, 0
	v_fma_f32 v217, -v141, v71, 0
	v_fma_f32 v214, -v142, v72, v214
	v_fma_f32 v215, -v143, v73, v215
	v_fma_f32 v216, -v144, v74, v216
	v_fma_f32 v217, -v145, v75, v217
	v_fma_f32 v214, -v146, v76, v214
	v_fma_f32 v215, -v147, v77, v215
	v_fma_f32 v216, -v148, v78, v216
	v_fma_f32 v217, -v149, v79, v217
	v_fma_f32 v214, -v150, v80, v214
	v_fma_f32 v215, -v151, v81, v215
	v_fma_f32 v216, -v152, v82, v216
	v_fma_f32 v217, -v153, v83, v217
	v_fma_f32 v214, -v154, v84, v214
	v_fma_f32 v215, -v155, v85, v215
	v_fma_f32 v216, -v156, v86, v216
	v_fma_f32 v217, -v157, v87, v217
	v_fma_f32 v214, -v158, v88, v214
	v_fma_f32 v215, -v159, v89, v215
	v_fma_f32 v216, -v160, v90, v216
	v_fma_f32 v217, -v161, v91, v217
	v_fma_f32 v214, -v162, v92, v214
	v_fma_f32 v215, -v163, v93, v215
	v_fma_f32 v216, -v164, v94, v216
	v_fma_f32 v217, -v165, v95, v217
	v_fma_f32 v214, -v166, v96, v214
	v_fma_f32 v215, -v167, v97, v215
	v_fma_f32 v216, -v168, v98, v216
	v_fma_f32 v217, -v169, v99, v217
	v_fma_f32 v214, -v170, v100, v214
	v_add_f32_e32 v214, v215, v214
	v_add_f32_e32 v215, v216, v217
	v_add_f32_e32 v171, v215, v214
	ds_write_b32 v218, v171 offset:34320
	s_waitcnt lgkmcnt(0)
	ds_read_b32 v213, v218 offset:36400
	ds_read_b128 v[68:71], v219 offset:8960
	ds_read_b128 v[72:75], v219 offset:8976
	ds_read_b128 v[76:79], v219 offset:8992
	ds_read_b128 v[80:83], v219 offset:9008
	ds_read_b128 v[84:87], v219 offset:9024
	ds_read_b128 v[88:91], v219 offset:9040
	ds_read_b128 v[92:95], v219 offset:9056
	ds_read_b128 v[96:99], v219 offset:9072
	ds_read_b128 v[100:103], v219 offset:9088
	v_fma_f32 v214, -v138, v0, v212
	v_fma_f32 v215, -v139, v1, 0
	v_fma_f32 v216, -v140, v2, 0
	v_fma_f32 v217, -v141, v3, 0
	v_fma_f32 v214, -v142, v4, v214
	v_fma_f32 v215, -v143, v5, v215
	v_fma_f32 v216, -v144, v6, v216
	v_fma_f32 v217, -v145, v7, v217
	v_fma_f32 v214, -v146, v8, v214
	v_fma_f32 v215, -v147, v9, v215
	v_fma_f32 v216, -v148, v10, v216
	v_fma_f32 v217, -v149, v11, v217
	v_fma_f32 v214, -v150, v12, v214
	v_fma_f32 v215, -v151, v13, v215
	v_fma_f32 v216, -v152, v14, v216
	v_fma_f32 v217, -v153, v15, v217
	v_fma_f32 v214, -v154, v18, v214
	v_fma_f32 v215, -v155, v19, v215
	v_fma_f32 v216, -v156, v20, v216
	v_fma_f32 v217, -v157, v21, v217
	v_fma_f32 v214, -v158, v22, v214
	v_fma_f32 v215, -v159, v23, v215
	v_fma_f32 v216, -v160, v24, v216
	v_fma_f32 v217, -v161, v25, v217
	v_fma_f32 v214, -v162, v26, v214
	v_fma_f32 v215, -v163, v27, v215
	v_fma_f32 v216, -v164, v28, v216
	v_fma_f32 v217, -v165, v29, v217
	v_fma_f32 v214, -v166, v30, v214
	v_fma_f32 v215, -v167, v31, v215
	v_fma_f32 v216, -v168, v32, v216
	v_fma_f32 v217, -v169, v33, v217
	v_fma_f32 v214, -v170, v34, v214
	v_fma_f32 v215, -v171, v35, v215
	v_add_f32_e32 v214, v215, v214
	v_add_f32_e32 v215, v216, v217
	v_add_f32_e32 v172, v215, v214
	ds_write_b32 v218, v172 offset:35360
	s_waitcnt lgkmcnt(0)
	ds_read_b32 v212, v218 offset:37440
	ds_read_b128 v[0:3], v219 offset:9216
	ds_read_b128 v[4:7], v219 offset:9232
	ds_read_b128 v[8:11], v219 offset:9248
	ds_read_b128 v[12:15], v219 offset:9264
	ds_read_b128 v[18:21], v219 offset:9280
	ds_read_b128 v[22:25], v219 offset:9296
	ds_read_b128 v[26:29], v219 offset:9312
	ds_read_b128 v[30:33], v219 offset:9328
	ds_read_b128 v[34:37], v219 offset:9344
	v_fma_f32 v214, -v138, v68, v213
	v_fma_f32 v215, -v139, v69, 0
	v_fma_f32 v216, -v140, v70, 0
	v_fma_f32 v217, -v141, v71, 0
	v_fma_f32 v214, -v142, v72, v214
	v_fma_f32 v215, -v143, v73, v215
	v_fma_f32 v216, -v144, v74, v216
	v_fma_f32 v217, -v145, v75, v217
	v_fma_f32 v214, -v146, v76, v214
	v_fma_f32 v215, -v147, v77, v215
	v_fma_f32 v216, -v148, v78, v216
	v_fma_f32 v217, -v149, v79, v217
	v_fma_f32 v214, -v150, v80, v214
	v_fma_f32 v215, -v151, v81, v215
	v_fma_f32 v216, -v152, v82, v216
	v_fma_f32 v217, -v153, v83, v217
	v_fma_f32 v214, -v154, v84, v214
	v_fma_f32 v215, -v155, v85, v215
	v_fma_f32 v216, -v156, v86, v216
	v_fma_f32 v217, -v157, v87, v217
	v_fma_f32 v214, -v158, v88, v214
	v_fma_f32 v215, -v159, v89, v215
	v_fma_f32 v216, -v160, v90, v216
	v_fma_f32 v217, -v161, v91, v217
	v_fma_f32 v214, -v162, v92, v214
	v_fma_f32 v215, -v163, v93, v215
	v_fma_f32 v216, -v164, v94, v216
	v_fma_f32 v217, -v165, v95, v217
	v_fma_f32 v214, -v166, v96, v214
	v_fma_f32 v215, -v167, v97, v215
	v_fma_f32 v216, -v168, v98, v216
	v_fma_f32 v217, -v169, v99, v217
	v_fma_f32 v214, -v170, v100, v214
	v_fma_f32 v215, -v171, v101, v215
	v_fma_f32 v216, -v172, v102, v216
	v_add_f32_e32 v214, v215, v214
	v_add_f32_e32 v215, v216, v217
	v_add_f32_e32 v173, v215, v214
	ds_write_b32 v218, v173 offset:36400
	s_waitcnt lgkmcnt(0)
	ds_read_b32 v213, v218 offset:38480
	ds_read_b128 v[68:71], v219 offset:9472
	ds_read_b128 v[72:75], v219 offset:9488
	ds_read_b128 v[76:79], v219 offset:9504
	ds_read_b128 v[80:83], v219 offset:9520
	ds_read_b128 v[84:87], v219 offset:9536
	ds_read_b128 v[88:91], v219 offset:9552
	ds_read_b128 v[92:95], v219 offset:9568
	ds_read_b128 v[96:99], v219 offset:9584
	ds_read_b128 v[100:103], v219 offset:9600
	ds_read_b128 v[108:111], v219 offset:9616
	v_fma_f32 v214, -v138, v0, v212
	v_fma_f32 v215, -v139, v1, 0
	v_fma_f32 v216, -v140, v2, 0
	v_fma_f32 v217, -v141, v3, 0
	v_fma_f32 v214, -v142, v4, v214
	v_fma_f32 v215, -v143, v5, v215
	v_fma_f32 v216, -v144, v6, v216
	v_fma_f32 v217, -v145, v7, v217
	v_fma_f32 v214, -v146, v8, v214
	v_fma_f32 v215, -v147, v9, v215
	v_fma_f32 v216, -v148, v10, v216
	v_fma_f32 v217, -v149, v11, v217
	v_fma_f32 v214, -v150, v12, v214
	v_fma_f32 v215, -v151, v13, v215
	v_fma_f32 v216, -v152, v14, v216
	v_fma_f32 v217, -v153, v15, v217
	v_fma_f32 v214, -v154, v18, v214
	v_fma_f32 v215, -v155, v19, v215
	v_fma_f32 v216, -v156, v20, v216
	v_fma_f32 v217, -v157, v21, v217
	v_fma_f32 v214, -v158, v22, v214
	v_fma_f32 v215, -v159, v23, v215
	v_fma_f32 v216, -v160, v24, v216
	v_fma_f32 v217, -v161, v25, v217
	v_fma_f32 v214, -v162, v26, v214
	v_fma_f32 v215, -v163, v27, v215
	v_fma_f32 v216, -v164, v28, v216
	v_fma_f32 v217, -v165, v29, v217
	v_fma_f32 v214, -v166, v30, v214
	v_fma_f32 v215, -v167, v31, v215
	v_fma_f32 v216, -v168, v32, v216
	v_fma_f32 v217, -v169, v33, v217
	v_fma_f32 v214, -v170, v34, v214
	v_fma_f32 v215, -v171, v35, v215
	v_fma_f32 v216, -v172, v36, v216
	v_fma_f32 v217, -v173, v37, v217
	v_add_f32_e32 v214, v215, v214
	v_add_f32_e32 v215, v216, v217
	v_add_f32_e32 v174, v215, v214
	ds_write_b32 v218, v174 offset:37440
	s_waitcnt lgkmcnt(0)
	ds_read_b32 v212, v218 offset:39520
	ds_read_b128 v[0:3], v219 offset:9728
	ds_read_b128 v[4:7], v219 offset:9744
	ds_read_b128 v[8:11], v219 offset:9760
	ds_read_b128 v[12:15], v219 offset:9776
	ds_read_b128 v[18:21], v219 offset:9792
	ds_read_b128 v[22:25], v219 offset:9808
	ds_read_b128 v[26:29], v219 offset:9824
	ds_read_b128 v[30:33], v219 offset:9840
	ds_read_b128 v[34:37], v219 offset:9856
	ds_read_b128 v[38:41], v219 offset:9872
	v_fma_f32 v214, -v138, v68, v213
	v_fma_f32 v215, -v139, v69, 0
	v_fma_f32 v216, -v140, v70, 0
	v_fma_f32 v217, -v141, v71, 0
	v_fma_f32 v214, -v142, v72, v214
	v_fma_f32 v215, -v143, v73, v215
	v_fma_f32 v216, -v144, v74, v216
	v_fma_f32 v217, -v145, v75, v217
	v_fma_f32 v214, -v146, v76, v214
	v_fma_f32 v215, -v147, v77, v215
	v_fma_f32 v216, -v148, v78, v216
	v_fma_f32 v217, -v149, v79, v217
	v_fma_f32 v214, -v150, v80, v214
	v_fma_f32 v215, -v151, v81, v215
	v_fma_f32 v216, -v152, v82, v216
	v_fma_f32 v217, -v153, v83, v217
	v_fma_f32 v214, -v154, v84, v214
	v_fma_f32 v215, -v155, v85, v215
	v_fma_f32 v216, -v156, v86, v216
	v_fma_f32 v217, -v157, v87, v217
	v_fma_f32 v214, -v158, v88, v214
	v_fma_f32 v215, -v159, v89, v215
	v_fma_f32 v216, -v160, v90, v216
	v_fma_f32 v217, -v161, v91, v217
	v_fma_f32 v214, -v162, v92, v214
	v_fma_f32 v215, -v163, v93, v215
	v_fma_f32 v216, -v164, v94, v216
	v_fma_f32 v217, -v165, v95, v217
	v_fma_f32 v214, -v166, v96, v214
	v_fma_f32 v215, -v167, v97, v215
	v_fma_f32 v216, -v168, v98, v216
	v_fma_f32 v217, -v169, v99, v217
	v_fma_f32 v214, -v170, v100, v214
	v_fma_f32 v215, -v171, v101, v215
	v_fma_f32 v216, -v172, v102, v216
	v_fma_f32 v217, -v173, v103, v217
	v_fma_f32 v214, -v174, v108, v214
	v_add_f32_e32 v214, v215, v214
	v_add_f32_e32 v215, v216, v217
	v_add_f32_e32 v175, v215, v214
	ds_write_b32 v218, v175 offset:38480
	s_waitcnt lgkmcnt(0)
	ds_read_b32 v213, v218 offset:40560
	ds_read_b128 v[68:71], v219 offset:9984
	ds_read_b128 v[72:75], v219 offset:10000
	ds_read_b128 v[76:79], v219 offset:10016
	ds_read_b128 v[80:83], v219 offset:10032
	ds_read_b128 v[84:87], v219 offset:10048
	ds_read_b128 v[88:91], v219 offset:10064
	ds_read_b128 v[92:95], v219 offset:10080
	ds_read_b128 v[96:99], v219 offset:10096
	ds_read_b128 v[100:103], v219 offset:10112
	ds_read_b128 v[108:111], v219 offset:10128
	v_fma_f32 v214, -v138, v0, v212
	v_fma_f32 v215, -v139, v1, 0
	v_fma_f32 v216, -v140, v2, 0
	v_fma_f32 v217, -v141, v3, 0
	v_fma_f32 v214, -v142, v4, v214
	v_fma_f32 v215, -v143, v5, v215
	v_fma_f32 v216, -v144, v6, v216
	v_fma_f32 v217, -v145, v7, v217
	v_fma_f32 v214, -v146, v8, v214
	v_fma_f32 v215, -v147, v9, v215
	v_fma_f32 v216, -v148, v10, v216
	v_fma_f32 v217, -v149, v11, v217
	v_fma_f32 v214, -v150, v12, v214
	v_fma_f32 v215, -v151, v13, v215
	v_fma_f32 v216, -v152, v14, v216
	v_fma_f32 v217, -v153, v15, v217
	v_fma_f32 v214, -v154, v18, v214
	v_fma_f32 v215, -v155, v19, v215
	v_fma_f32 v216, -v156, v20, v216
	v_fma_f32 v217, -v157, v21, v217
	v_fma_f32 v214, -v158, v22, v214
	v_fma_f32 v215, -v159, v23, v215
	v_fma_f32 v216, -v160, v24, v216
	v_fma_f32 v217, -v161, v25, v217
	v_fma_f32 v214, -v162, v26, v214
	v_fma_f32 v215, -v163, v27, v215
	v_fma_f32 v216, -v164, v28, v216
	v_fma_f32 v217, -v165, v29, v217
	v_fma_f32 v214, -v166, v30, v214
	v_fma_f32 v215, -v167, v31, v215
	v_fma_f32 v216, -v168, v32, v216
	v_fma_f32 v217, -v169, v33, v217
	v_fma_f32 v214, -v170, v34, v214
	v_fma_f32 v215, -v171, v35, v215
	v_fma_f32 v216, -v172, v36, v216
	v_fma_f32 v217, -v173, v37, v217
	v_fma_f32 v214, -v174, v38, v214
	v_fma_f32 v215, -v175, v39, v215
	v_add_f32_e32 v214, v215, v214
	v_add_f32_e32 v215, v216, v217
	v_add_f32_e32 v176, v215, v214
	ds_write_b32 v218, v176 offset:39520
	s_waitcnt lgkmcnt(0)
	ds_read_b32 v212, v218 offset:41600
	ds_read_b128 v[0:3], v219 offset:10240
	ds_read_b128 v[4:7], v219 offset:10256
	ds_read_b128 v[8:11], v219 offset:10272
	ds_read_b128 v[12:15], v219 offset:10288
	ds_read_b128 v[18:21], v219 offset:10304
	ds_read_b128 v[22:25], v219 offset:10320
	ds_read_b128 v[26:29], v219 offset:10336
	ds_read_b128 v[30:33], v219 offset:10352
	ds_read_b128 v[34:37], v219 offset:10368
	ds_read_b128 v[38:41], v219 offset:10384
	v_fma_f32 v214, -v138, v68, v213
	v_fma_f32 v215, -v139, v69, 0
	v_fma_f32 v216, -v140, v70, 0
	v_fma_f32 v217, -v141, v71, 0
	v_fma_f32 v214, -v142, v72, v214
	v_fma_f32 v215, -v143, v73, v215
	v_fma_f32 v216, -v144, v74, v216
	v_fma_f32 v217, -v145, v75, v217
	v_fma_f32 v214, -v146, v76, v214
	v_fma_f32 v215, -v147, v77, v215
	v_fma_f32 v216, -v148, v78, v216
	v_fma_f32 v217, -v149, v79, v217
	v_fma_f32 v214, -v150, v80, v214
	v_fma_f32 v215, -v151, v81, v215
	v_fma_f32 v216, -v152, v82, v216
	v_fma_f32 v217, -v153, v83, v217
	v_fma_f32 v214, -v154, v84, v214
	v_fma_f32 v215, -v155, v85, v215
	v_fma_f32 v216, -v156, v86, v216
	v_fma_f32 v217, -v157, v87, v217
	v_fma_f32 v214, -v158, v88, v214
	v_fma_f32 v215, -v159, v89, v215
	v_fma_f32 v216, -v160, v90, v216
	v_fma_f32 v217, -v161, v91, v217
	v_fma_f32 v214, -v162, v92, v214
	v_fma_f32 v215, -v163, v93, v215
	v_fma_f32 v216, -v164, v94, v216
	v_fma_f32 v217, -v165, v95, v217
	v_fma_f32 v214, -v166, v96, v214
	v_fma_f32 v215, -v167, v97, v215
	v_fma_f32 v216, -v168, v98, v216
	v_fma_f32 v217, -v169, v99, v217
	v_fma_f32 v214, -v170, v100, v214
	v_fma_f32 v215, -v171, v101, v215
	v_fma_f32 v216, -v172, v102, v216
	v_fma_f32 v217, -v173, v103, v217
	v_fma_f32 v214, -v174, v108, v214
	v_fma_f32 v215, -v175, v109, v215
	v_fma_f32 v216, -v176, v110, v216
	v_add_f32_e32 v214, v215, v214
	v_add_f32_e32 v215, v216, v217
	v_add_f32_e32 v177, v215, v214
	ds_write_b32 v218, v177 offset:40560
	s_waitcnt lgkmcnt(0)
	ds_read_b32 v213, v218 offset:42640
	ds_read_b128 v[68:71], v219 offset:10496
	ds_read_b128 v[72:75], v219 offset:10512
	ds_read_b128 v[76:79], v219 offset:10528
	ds_read_b128 v[80:83], v219 offset:10544
	ds_read_b128 v[84:87], v219 offset:10560
	ds_read_b128 v[88:91], v219 offset:10576
	ds_read_b128 v[92:95], v219 offset:10592
	ds_read_b128 v[96:99], v219 offset:10608
	ds_read_b128 v[100:103], v219 offset:10624
	ds_read_b128 v[108:111], v219 offset:10640
	ds_read_b128 v[112:115], v219 offset:10656
	v_fma_f32 v214, -v138, v0, v212
	v_fma_f32 v215, -v139, v1, 0
	v_fma_f32 v216, -v140, v2, 0
	v_fma_f32 v217, -v141, v3, 0
	v_fma_f32 v214, -v142, v4, v214
	v_fma_f32 v215, -v143, v5, v215
	v_fma_f32 v216, -v144, v6, v216
	v_fma_f32 v217, -v145, v7, v217
	v_fma_f32 v214, -v146, v8, v214
	v_fma_f32 v215, -v147, v9, v215
	v_fma_f32 v216, -v148, v10, v216
	v_fma_f32 v217, -v149, v11, v217
	v_fma_f32 v214, -v150, v12, v214
	v_fma_f32 v215, -v151, v13, v215
	v_fma_f32 v216, -v152, v14, v216
	v_fma_f32 v217, -v153, v15, v217
	v_fma_f32 v214, -v154, v18, v214
	v_fma_f32 v215, -v155, v19, v215
	v_fma_f32 v216, -v156, v20, v216
	v_fma_f32 v217, -v157, v21, v217
	v_fma_f32 v214, -v158, v22, v214
	v_fma_f32 v215, -v159, v23, v215
	v_fma_f32 v216, -v160, v24, v216
	v_fma_f32 v217, -v161, v25, v217
	v_fma_f32 v214, -v162, v26, v214
	v_fma_f32 v215, -v163, v27, v215
	v_fma_f32 v216, -v164, v28, v216
	v_fma_f32 v217, -v165, v29, v217
	v_fma_f32 v214, -v166, v30, v214
	v_fma_f32 v215, -v167, v31, v215
	v_fma_f32 v216, -v168, v32, v216
	v_fma_f32 v217, -v169, v33, v217
	v_fma_f32 v214, -v170, v34, v214
	v_fma_f32 v215, -v171, v35, v215
	v_fma_f32 v216, -v172, v36, v216
	v_fma_f32 v217, -v173, v37, v217
	v_fma_f32 v214, -v174, v38, v214
	v_fma_f32 v215, -v175, v39, v215
	v_fma_f32 v216, -v176, v40, v216
	v_fma_f32 v217, -v177, v41, v217
	v_add_f32_e32 v214, v215, v214
	v_add_f32_e32 v215, v216, v217
	v_add_f32_e32 v178, v215, v214
	ds_write_b32 v218, v178 offset:41600
	s_waitcnt lgkmcnt(0)
	ds_read_b32 v212, v218 offset:43680
	ds_read_b128 v[0:3], v219 offset:10752
	ds_read_b128 v[4:7], v219 offset:10768
	ds_read_b128 v[8:11], v219 offset:10784
	ds_read_b128 v[12:15], v219 offset:10800
	ds_read_b128 v[18:21], v219 offset:10816
	ds_read_b128 v[22:25], v219 offset:10832
	ds_read_b128 v[26:29], v219 offset:10848
	ds_read_b128 v[30:33], v219 offset:10864
	ds_read_b128 v[34:37], v219 offset:10880
	ds_read_b128 v[38:41], v219 offset:10896
	ds_read_b128 v[42:45], v219 offset:10912
	v_fma_f32 v214, -v138, v68, v213
	v_fma_f32 v215, -v139, v69, 0
	v_fma_f32 v216, -v140, v70, 0
	v_fma_f32 v217, -v141, v71, 0
	v_fma_f32 v214, -v142, v72, v214
	v_fma_f32 v215, -v143, v73, v215
	v_fma_f32 v216, -v144, v74, v216
	v_fma_f32 v217, -v145, v75, v217
	v_fma_f32 v214, -v146, v76, v214
	v_fma_f32 v215, -v147, v77, v215
	v_fma_f32 v216, -v148, v78, v216
	v_fma_f32 v217, -v149, v79, v217
	v_fma_f32 v214, -v150, v80, v214
	v_fma_f32 v215, -v151, v81, v215
	v_fma_f32 v216, -v152, v82, v216
	v_fma_f32 v217, -v153, v83, v217
	v_fma_f32 v214, -v154, v84, v214
	v_fma_f32 v215, -v155, v85, v215
	v_fma_f32 v216, -v156, v86, v216
	v_fma_f32 v217, -v157, v87, v217
	v_fma_f32 v214, -v158, v88, v214
	v_fma_f32 v215, -v159, v89, v215
	v_fma_f32 v216, -v160, v90, v216
	v_fma_f32 v217, -v161, v91, v217
	v_fma_f32 v214, -v162, v92, v214
	v_fma_f32 v215, -v163, v93, v215
	v_fma_f32 v216, -v164, v94, v216
	v_fma_f32 v217, -v165, v95, v217
	v_fma_f32 v214, -v166, v96, v214
	v_fma_f32 v215, -v167, v97, v215
	v_fma_f32 v216, -v168, v98, v216
	v_fma_f32 v217, -v169, v99, v217
	v_fma_f32 v214, -v170, v100, v214
	v_fma_f32 v215, -v171, v101, v215
	v_fma_f32 v216, -v172, v102, v216
	v_fma_f32 v217, -v173, v103, v217
	v_fma_f32 v214, -v174, v108, v214
	v_fma_f32 v215, -v175, v109, v215
	v_fma_f32 v216, -v176, v110, v216
	v_fma_f32 v217, -v177, v111, v217
	v_fma_f32 v214, -v178, v112, v214
	v_add_f32_e32 v214, v215, v214
	v_add_f32_e32 v215, v216, v217
	v_add_f32_e32 v179, v215, v214
	ds_write_b32 v218, v179 offset:42640
	s_waitcnt lgkmcnt(0)
	ds_read_b32 v213, v218 offset:44720
	ds_read_b128 v[68:71], v219 offset:11008
	ds_read_b128 v[72:75], v219 offset:11024
	ds_read_b128 v[76:79], v219 offset:11040
	ds_read_b128 v[80:83], v219 offset:11056
	ds_read_b128 v[84:87], v219 offset:11072
	ds_read_b128 v[88:91], v219 offset:11088
	ds_read_b128 v[92:95], v219 offset:11104
	ds_read_b128 v[96:99], v219 offset:11120
	ds_read_b128 v[100:103], v219 offset:11136
	ds_read_b128 v[108:111], v219 offset:11152
	ds_read_b128 v[112:115], v219 offset:11168
	v_fma_f32 v214, -v138, v0, v212
	v_fma_f32 v215, -v139, v1, 0
	v_fma_f32 v216, -v140, v2, 0
	v_fma_f32 v217, -v141, v3, 0
	v_fma_f32 v214, -v142, v4, v214
	v_fma_f32 v215, -v143, v5, v215
	v_fma_f32 v216, -v144, v6, v216
	v_fma_f32 v217, -v145, v7, v217
	v_fma_f32 v214, -v146, v8, v214
	v_fma_f32 v215, -v147, v9, v215
	v_fma_f32 v216, -v148, v10, v216
	v_fma_f32 v217, -v149, v11, v217
	v_fma_f32 v214, -v150, v12, v214
	v_fma_f32 v215, -v151, v13, v215
	v_fma_f32 v216, -v152, v14, v216
	v_fma_f32 v217, -v153, v15, v217
	v_fma_f32 v214, -v154, v18, v214
	v_fma_f32 v215, -v155, v19, v215
	v_fma_f32 v216, -v156, v20, v216
	v_fma_f32 v217, -v157, v21, v217
	v_fma_f32 v214, -v158, v22, v214
	v_fma_f32 v215, -v159, v23, v215
	v_fma_f32 v216, -v160, v24, v216
	v_fma_f32 v217, -v161, v25, v217
	v_fma_f32 v214, -v162, v26, v214
	v_fma_f32 v215, -v163, v27, v215
	v_fma_f32 v216, -v164, v28, v216
	v_fma_f32 v217, -v165, v29, v217
	v_fma_f32 v214, -v166, v30, v214
	v_fma_f32 v215, -v167, v31, v215
	v_fma_f32 v216, -v168, v32, v216
	v_fma_f32 v217, -v169, v33, v217
	v_fma_f32 v214, -v170, v34, v214
	v_fma_f32 v215, -v171, v35, v215
	v_fma_f32 v216, -v172, v36, v216
	v_fma_f32 v217, -v173, v37, v217
	v_fma_f32 v214, -v174, v38, v214
	v_fma_f32 v215, -v175, v39, v215
	v_fma_f32 v216, -v176, v40, v216
	v_fma_f32 v217, -v177, v41, v217
	v_fma_f32 v214, -v178, v42, v214
	v_fma_f32 v215, -v179, v43, v215
	v_add_f32_e32 v214, v215, v214
	v_add_f32_e32 v215, v216, v217
	v_add_f32_e32 v180, v215, v214
	ds_write_b32 v218, v180 offset:43680
	s_waitcnt lgkmcnt(0)
	ds_read_b32 v212, v218 offset:45760
	ds_read_b128 v[0:3], v219 offset:11264
	ds_read_b128 v[4:7], v219 offset:11280
	ds_read_b128 v[8:11], v219 offset:11296
	ds_read_b128 v[12:15], v219 offset:11312
	ds_read_b128 v[18:21], v219 offset:11328
	ds_read_b128 v[22:25], v219 offset:11344
	ds_read_b128 v[26:29], v219 offset:11360
	ds_read_b128 v[30:33], v219 offset:11376
	ds_read_b128 v[34:37], v219 offset:11392
	ds_read_b128 v[38:41], v219 offset:11408
	ds_read_b128 v[42:45], v219 offset:11424
	v_fma_f32 v214, -v138, v68, v213
	v_fma_f32 v215, -v139, v69, 0
	v_fma_f32 v216, -v140, v70, 0
	v_fma_f32 v217, -v141, v71, 0
	v_fma_f32 v214, -v142, v72, v214
	v_fma_f32 v215, -v143, v73, v215
	v_fma_f32 v216, -v144, v74, v216
	v_fma_f32 v217, -v145, v75, v217
	v_fma_f32 v214, -v146, v76, v214
	v_fma_f32 v215, -v147, v77, v215
	v_fma_f32 v216, -v148, v78, v216
	v_fma_f32 v217, -v149, v79, v217
	v_fma_f32 v214, -v150, v80, v214
	v_fma_f32 v215, -v151, v81, v215
	v_fma_f32 v216, -v152, v82, v216
	v_fma_f32 v217, -v153, v83, v217
	v_fma_f32 v214, -v154, v84, v214
	v_fma_f32 v215, -v155, v85, v215
	v_fma_f32 v216, -v156, v86, v216
	v_fma_f32 v217, -v157, v87, v217
	v_fma_f32 v214, -v158, v88, v214
	v_fma_f32 v215, -v159, v89, v215
	v_fma_f32 v216, -v160, v90, v216
	v_fma_f32 v217, -v161, v91, v217
	v_fma_f32 v214, -v162, v92, v214
	v_fma_f32 v215, -v163, v93, v215
	v_fma_f32 v216, -v164, v94, v216
	v_fma_f32 v217, -v165, v95, v217
	v_fma_f32 v214, -v166, v96, v214
	v_fma_f32 v215, -v167, v97, v215
	v_fma_f32 v216, -v168, v98, v216
	v_fma_f32 v217, -v169, v99, v217
	v_fma_f32 v214, -v170, v100, v214
	v_fma_f32 v215, -v171, v101, v215
	v_fma_f32 v216, -v172, v102, v216
	v_fma_f32 v217, -v173, v103, v217
	v_fma_f32 v214, -v174, v108, v214
	v_fma_f32 v215, -v175, v109, v215
	v_fma_f32 v216, -v176, v110, v216
	v_fma_f32 v217, -v177, v111, v217
	v_fma_f32 v214, -v178, v112, v214
	v_fma_f32 v215, -v179, v113, v215
	v_fma_f32 v216, -v180, v114, v216
	v_add_f32_e32 v214, v215, v214
	v_add_f32_e32 v215, v216, v217
	v_add_f32_e32 v181, v215, v214
	ds_write_b32 v218, v181 offset:44720
	s_waitcnt lgkmcnt(0)
	ds_read_b32 v213, v218 offset:46800
	ds_read_b128 v[68:71], v219 offset:11520
	ds_read_b128 v[72:75], v219 offset:11536
	ds_read_b128 v[76:79], v219 offset:11552
	ds_read_b128 v[80:83], v219 offset:11568
	ds_read_b128 v[84:87], v219 offset:11584
	ds_read_b128 v[88:91], v219 offset:11600
	ds_read_b128 v[92:95], v219 offset:11616
	ds_read_b128 v[96:99], v219 offset:11632
	ds_read_b128 v[100:103], v219 offset:11648
	ds_read_b128 v[108:111], v219 offset:11664
	ds_read_b128 v[112:115], v219 offset:11680
	ds_read_b128 v[116:119], v219 offset:11696
	v_fma_f32 v214, -v138, v0, v212
	v_fma_f32 v215, -v139, v1, 0
	v_fma_f32 v216, -v140, v2, 0
	v_fma_f32 v217, -v141, v3, 0
	v_fma_f32 v214, -v142, v4, v214
	v_fma_f32 v215, -v143, v5, v215
	v_fma_f32 v216, -v144, v6, v216
	v_fma_f32 v217, -v145, v7, v217
	v_fma_f32 v214, -v146, v8, v214
	v_fma_f32 v215, -v147, v9, v215
	v_fma_f32 v216, -v148, v10, v216
	v_fma_f32 v217, -v149, v11, v217
	v_fma_f32 v214, -v150, v12, v214
	v_fma_f32 v215, -v151, v13, v215
	v_fma_f32 v216, -v152, v14, v216
	v_fma_f32 v217, -v153, v15, v217
	v_fma_f32 v214, -v154, v18, v214
	v_fma_f32 v215, -v155, v19, v215
	v_fma_f32 v216, -v156, v20, v216
	v_fma_f32 v217, -v157, v21, v217
	v_fma_f32 v214, -v158, v22, v214
	v_fma_f32 v215, -v159, v23, v215
	v_fma_f32 v216, -v160, v24, v216
	v_fma_f32 v217, -v161, v25, v217
	v_fma_f32 v214, -v162, v26, v214
	v_fma_f32 v215, -v163, v27, v215
	v_fma_f32 v216, -v164, v28, v216
	v_fma_f32 v217, -v165, v29, v217
	v_fma_f32 v214, -v166, v30, v214
	v_fma_f32 v215, -v167, v31, v215
	v_fma_f32 v216, -v168, v32, v216
	v_fma_f32 v217, -v169, v33, v217
	v_fma_f32 v214, -v170, v34, v214
	v_fma_f32 v215, -v171, v35, v215
	v_fma_f32 v216, -v172, v36, v216
	v_fma_f32 v217, -v173, v37, v217
	v_fma_f32 v214, -v174, v38, v214
	v_fma_f32 v215, -v175, v39, v215
	v_fma_f32 v216, -v176, v40, v216
	v_fma_f32 v217, -v177, v41, v217
	v_fma_f32 v214, -v178, v42, v214
	v_fma_f32 v215, -v179, v43, v215
	v_fma_f32 v216, -v180, v44, v216
	v_fma_f32 v217, -v181, v45, v217
	v_add_f32_e32 v214, v215, v214
	v_add_f32_e32 v215, v216, v217
	v_add_f32_e32 v182, v215, v214
	ds_write_b32 v218, v182 offset:45760
	s_waitcnt lgkmcnt(0)
	ds_read_b32 v212, v218 offset:47840
	ds_read_b128 v[0:3], v219 offset:11776
	ds_read_b128 v[4:7], v219 offset:11792
	ds_read_b128 v[8:11], v219 offset:11808
	ds_read_b128 v[12:15], v219 offset:11824
	ds_read_b128 v[18:21], v219 offset:11840
	ds_read_b128 v[22:25], v219 offset:11856
	ds_read_b128 v[26:29], v219 offset:11872
	ds_read_b128 v[30:33], v219 offset:11888
	ds_read_b128 v[34:37], v219 offset:11904
	ds_read_b128 v[38:41], v219 offset:11920
	ds_read_b128 v[42:45], v219 offset:11936
	ds_read_b128 v[46:49], v219 offset:11952
	v_fma_f32 v214, -v138, v68, v213
	v_fma_f32 v215, -v139, v69, 0
	v_fma_f32 v216, -v140, v70, 0
	v_fma_f32 v217, -v141, v71, 0
	v_fma_f32 v214, -v142, v72, v214
	v_fma_f32 v215, -v143, v73, v215
	v_fma_f32 v216, -v144, v74, v216
	v_fma_f32 v217, -v145, v75, v217
	v_fma_f32 v214, -v146, v76, v214
	v_fma_f32 v215, -v147, v77, v215
	v_fma_f32 v216, -v148, v78, v216
	v_fma_f32 v217, -v149, v79, v217
	v_fma_f32 v214, -v150, v80, v214
	v_fma_f32 v215, -v151, v81, v215
	v_fma_f32 v216, -v152, v82, v216
	v_fma_f32 v217, -v153, v83, v217
	v_fma_f32 v214, -v154, v84, v214
	v_fma_f32 v215, -v155, v85, v215
	v_fma_f32 v216, -v156, v86, v216
	v_fma_f32 v217, -v157, v87, v217
	v_fma_f32 v214, -v158, v88, v214
	v_fma_f32 v215, -v159, v89, v215
	v_fma_f32 v216, -v160, v90, v216
	v_fma_f32 v217, -v161, v91, v217
	v_fma_f32 v214, -v162, v92, v214
	v_fma_f32 v215, -v163, v93, v215
	v_fma_f32 v216, -v164, v94, v216
	v_fma_f32 v217, -v165, v95, v217
	v_fma_f32 v214, -v166, v96, v214
	v_fma_f32 v215, -v167, v97, v215
	v_fma_f32 v216, -v168, v98, v216
	v_fma_f32 v217, -v169, v99, v217
	v_fma_f32 v214, -v170, v100, v214
	v_fma_f32 v215, -v171, v101, v215
	v_fma_f32 v216, -v172, v102, v216
	v_fma_f32 v217, -v173, v103, v217
	v_fma_f32 v214, -v174, v108, v214
	v_fma_f32 v215, -v175, v109, v215
	v_fma_f32 v216, -v176, v110, v216
	v_fma_f32 v217, -v177, v111, v217
	v_fma_f32 v214, -v178, v112, v214
	v_fma_f32 v215, -v179, v113, v215
	v_fma_f32 v216, -v180, v114, v216
	v_fma_f32 v217, -v181, v115, v217
	v_fma_f32 v214, -v182, v116, v214
	v_add_f32_e32 v214, v215, v214
	v_add_f32_e32 v215, v216, v217
	v_add_f32_e32 v183, v215, v214
	ds_write_b32 v218, v183 offset:46800
	s_waitcnt lgkmcnt(0)
	ds_read_b32 v213, v218 offset:48880
	ds_read_b128 v[68:71], v219 offset:12032
	ds_read_b128 v[72:75], v219 offset:12048
	ds_read_b128 v[76:79], v219 offset:12064
	ds_read_b128 v[80:83], v219 offset:12080
	ds_read_b128 v[84:87], v219 offset:12096
	ds_read_b128 v[88:91], v219 offset:12112
	ds_read_b128 v[92:95], v219 offset:12128
	ds_read_b128 v[96:99], v219 offset:12144
	ds_read_b128 v[100:103], v219 offset:12160
	ds_read_b128 v[108:111], v219 offset:12176
	ds_read_b128 v[112:115], v219 offset:12192
	ds_read_b128 v[116:119], v219 offset:12208
	v_fma_f32 v214, -v138, v0, v212
	v_fma_f32 v215, -v139, v1, 0
	v_fma_f32 v216, -v140, v2, 0
	v_fma_f32 v217, -v141, v3, 0
	v_fma_f32 v214, -v142, v4, v214
	v_fma_f32 v215, -v143, v5, v215
	v_fma_f32 v216, -v144, v6, v216
	v_fma_f32 v217, -v145, v7, v217
	v_fma_f32 v214, -v146, v8, v214
	v_fma_f32 v215, -v147, v9, v215
	v_fma_f32 v216, -v148, v10, v216
	v_fma_f32 v217, -v149, v11, v217
	v_fma_f32 v214, -v150, v12, v214
	v_fma_f32 v215, -v151, v13, v215
	v_fma_f32 v216, -v152, v14, v216
	v_fma_f32 v217, -v153, v15, v217
	v_fma_f32 v214, -v154, v18, v214
	v_fma_f32 v215, -v155, v19, v215
	v_fma_f32 v216, -v156, v20, v216
	v_fma_f32 v217, -v157, v21, v217
	v_fma_f32 v214, -v158, v22, v214
	v_fma_f32 v215, -v159, v23, v215
	v_fma_f32 v216, -v160, v24, v216
	v_fma_f32 v217, -v161, v25, v217
	v_fma_f32 v214, -v162, v26, v214
	v_fma_f32 v215, -v163, v27, v215
	v_fma_f32 v216, -v164, v28, v216
	v_fma_f32 v217, -v165, v29, v217
	v_fma_f32 v214, -v166, v30, v214
	v_fma_f32 v215, -v167, v31, v215
	v_fma_f32 v216, -v168, v32, v216
	v_fma_f32 v217, -v169, v33, v217
	v_fma_f32 v214, -v170, v34, v214
	v_fma_f32 v215, -v171, v35, v215
	v_fma_f32 v216, -v172, v36, v216
	v_fma_f32 v217, -v173, v37, v217
	v_fma_f32 v214, -v174, v38, v214
	v_fma_f32 v215, -v175, v39, v215
	v_fma_f32 v216, -v176, v40, v216
	v_fma_f32 v217, -v177, v41, v217
	v_fma_f32 v214, -v178, v42, v214
	v_fma_f32 v215, -v179, v43, v215
	v_fma_f32 v216, -v180, v44, v216
	v_fma_f32 v217, -v181, v45, v217
	v_fma_f32 v214, -v182, v46, v214
	v_fma_f32 v215, -v183, v47, v215
	v_add_f32_e32 v214, v215, v214
	v_add_f32_e32 v215, v216, v217
	v_add_f32_e32 v184, v215, v214
	ds_write_b32 v218, v184 offset:47840
	s_waitcnt lgkmcnt(0)
	ds_read_b32 v212, v218 offset:49920
	ds_read_b128 v[0:3], v219 offset:12288
	ds_read_b128 v[4:7], v219 offset:12304
	ds_read_b128 v[8:11], v219 offset:12320
	ds_read_b128 v[12:15], v219 offset:12336
	ds_read_b128 v[18:21], v219 offset:12352
	ds_read_b128 v[22:25], v219 offset:12368
	ds_read_b128 v[26:29], v219 offset:12384
	ds_read_b128 v[30:33], v219 offset:12400
	ds_read_b128 v[34:37], v219 offset:12416
	ds_read_b128 v[38:41], v219 offset:12432
	ds_read_b128 v[42:45], v219 offset:12448
	ds_read_b128 v[46:49], v219 offset:12464
	v_fma_f32 v214, -v138, v68, v213
	v_fma_f32 v215, -v139, v69, 0
	v_fma_f32 v216, -v140, v70, 0
	v_fma_f32 v217, -v141, v71, 0
	v_fma_f32 v214, -v142, v72, v214
	v_fma_f32 v215, -v143, v73, v215
	v_fma_f32 v216, -v144, v74, v216
	v_fma_f32 v217, -v145, v75, v217
	v_fma_f32 v214, -v146, v76, v214
	v_fma_f32 v215, -v147, v77, v215
	v_fma_f32 v216, -v148, v78, v216
	v_fma_f32 v217, -v149, v79, v217
	v_fma_f32 v214, -v150, v80, v214
	v_fma_f32 v215, -v151, v81, v215
	v_fma_f32 v216, -v152, v82, v216
	v_fma_f32 v217, -v153, v83, v217
	v_fma_f32 v214, -v154, v84, v214
	v_fma_f32 v215, -v155, v85, v215
	v_fma_f32 v216, -v156, v86, v216
	v_fma_f32 v217, -v157, v87, v217
	v_fma_f32 v214, -v158, v88, v214
	v_fma_f32 v215, -v159, v89, v215
	v_fma_f32 v216, -v160, v90, v216
	v_fma_f32 v217, -v161, v91, v217
	v_fma_f32 v214, -v162, v92, v214
	v_fma_f32 v215, -v163, v93, v215
	v_fma_f32 v216, -v164, v94, v216
	v_fma_f32 v217, -v165, v95, v217
	v_fma_f32 v214, -v166, v96, v214
	v_fma_f32 v215, -v167, v97, v215
	v_fma_f32 v216, -v168, v98, v216
	v_fma_f32 v217, -v169, v99, v217
	v_fma_f32 v214, -v170, v100, v214
	v_fma_f32 v215, -v171, v101, v215
	v_fma_f32 v216, -v172, v102, v216
	v_fma_f32 v217, -v173, v103, v217
	v_fma_f32 v214, -v174, v108, v214
	v_fma_f32 v215, -v175, v109, v215
	v_fma_f32 v216, -v176, v110, v216
	v_fma_f32 v217, -v177, v111, v217
	v_fma_f32 v214, -v178, v112, v214
	v_fma_f32 v215, -v179, v113, v215
	v_fma_f32 v216, -v180, v114, v216
	v_fma_f32 v217, -v181, v115, v217
	v_fma_f32 v214, -v182, v116, v214
	v_fma_f32 v215, -v183, v117, v215
	v_fma_f32 v216, -v184, v118, v216
	v_add_f32_e32 v214, v215, v214
	v_add_f32_e32 v215, v216, v217
	v_add_f32_e32 v185, v215, v214
	ds_write_b32 v218, v185 offset:48880
	s_waitcnt lgkmcnt(0)
	ds_read_b32 v213, v218 offset:50960
	ds_read_b128 v[68:71], v219 offset:12544
	ds_read_b128 v[72:75], v219 offset:12560
	ds_read_b128 v[76:79], v219 offset:12576
	ds_read_b128 v[80:83], v219 offset:12592
	ds_read_b128 v[84:87], v219 offset:12608
	ds_read_b128 v[88:91], v219 offset:12624
	ds_read_b128 v[92:95], v219 offset:12640
	ds_read_b128 v[96:99], v219 offset:12656
	ds_read_b128 v[100:103], v219 offset:12672
	ds_read_b128 v[108:111], v219 offset:12688
	ds_read_b128 v[112:115], v219 offset:12704
	v_fma_f32 v214, -v138, v0, v212
	v_fma_f32 v215, -v139, v1, 0
	v_fma_f32 v216, -v140, v2, 0
	v_fma_f32 v217, -v141, v3, 0
	v_fma_f32 v214, -v142, v4, v214
	v_fma_f32 v215, -v143, v5, v215
	v_fma_f32 v216, -v144, v6, v216
	v_fma_f32 v217, -v145, v7, v217
	v_fma_f32 v214, -v146, v8, v214
	v_fma_f32 v215, -v147, v9, v215
	v_fma_f32 v216, -v148, v10, v216
	v_fma_f32 v217, -v149, v11, v217
	v_fma_f32 v214, -v150, v12, v214
	v_fma_f32 v215, -v151, v13, v215
	v_fma_f32 v216, -v152, v14, v216
	v_fma_f32 v217, -v153, v15, v217
	v_fma_f32 v214, -v154, v18, v214
	v_fma_f32 v215, -v155, v19, v215
	v_fma_f32 v216, -v156, v20, v216
	v_fma_f32 v217, -v157, v21, v217
	v_fma_f32 v214, -v158, v22, v214
	v_fma_f32 v215, -v159, v23, v215
	v_fma_f32 v216, -v160, v24, v216
	v_fma_f32 v217, -v161, v25, v217
	s_waitcnt lgkmcnt(4)
	ds_read_b128 v[116:119], v219 offset:12720
	ds_read_b128 v[120:123], v219 offset:12736
	v_fma_f32 v214, -v162, v26, v214
	v_fma_f32 v215, -v163, v27, v215
	v_fma_f32 v216, -v164, v28, v216
	v_fma_f32 v217, -v165, v29, v217
	v_fma_f32 v214, -v166, v30, v214
	v_fma_f32 v215, -v167, v31, v215
	v_fma_f32 v216, -v168, v32, v216
	v_fma_f32 v217, -v169, v33, v217
	v_fma_f32 v214, -v170, v34, v214
	v_fma_f32 v215, -v171, v35, v215
	v_fma_f32 v216, -v172, v36, v216
	v_fma_f32 v217, -v173, v37, v217
	v_fma_f32 v214, -v174, v38, v214
	v_fma_f32 v215, -v175, v39, v215
	v_fma_f32 v216, -v176, v40, v216
	v_fma_f32 v217, -v177, v41, v217
	v_fma_f32 v214, -v178, v42, v214
	v_fma_f32 v215, -v179, v43, v215
	v_fma_f32 v216, -v180, v44, v216
	v_fma_f32 v217, -v181, v45, v217
	v_fma_f32 v214, -v182, v46, v214
	v_fma_f32 v215, -v183, v47, v215
	v_fma_f32 v216, -v184, v48, v216
	v_fma_f32 v217, -v185, v49, v217
	v_add_f32_e32 v214, v215, v214
	v_add_f32_e32 v215, v216, v217
	v_add_f32_e32 v186, v215, v214
	ds_write_b32 v218, v186 offset:49920
	s_waitcnt lgkmcnt(0)
	ds_read_b32 v212, v218 offset:52000
	ds_read_b128 v[0:3], v219 offset:12800
	ds_read_b128 v[4:7], v219 offset:12816
	ds_read_b128 v[8:11], v219 offset:12832
	ds_read_b128 v[12:15], v219 offset:12848
	ds_read_b128 v[18:21], v219 offset:12864
	ds_read_b128 v[22:25], v219 offset:12880
	ds_read_b128 v[26:29], v219 offset:12896
	ds_read_b128 v[30:33], v219 offset:12912
	ds_read_b128 v[34:37], v219 offset:12928
	ds_read_b128 v[38:41], v219 offset:12944
	ds_read_b128 v[42:45], v219 offset:12960
	v_fma_f32 v214, -v138, v68, v213
	v_fma_f32 v215, -v139, v69, 0
	v_fma_f32 v216, -v140, v70, 0
	v_fma_f32 v217, -v141, v71, 0
	v_fma_f32 v214, -v142, v72, v214
	v_fma_f32 v215, -v143, v73, v215
	v_fma_f32 v216, -v144, v74, v216
	v_fma_f32 v217, -v145, v75, v217
	v_fma_f32 v214, -v146, v76, v214
	v_fma_f32 v215, -v147, v77, v215
	v_fma_f32 v216, -v148, v78, v216
	v_fma_f32 v217, -v149, v79, v217
	v_fma_f32 v214, -v150, v80, v214
	v_fma_f32 v215, -v151, v81, v215
	v_fma_f32 v216, -v152, v82, v216
	v_fma_f32 v217, -v153, v83, v217
	v_fma_f32 v214, -v154, v84, v214
	v_fma_f32 v215, -v155, v85, v215
	v_fma_f32 v216, -v156, v86, v216
	v_fma_f32 v217, -v157, v87, v217
	v_fma_f32 v214, -v158, v88, v214
	v_fma_f32 v215, -v159, v89, v215
	v_fma_f32 v216, -v160, v90, v216
	v_fma_f32 v217, -v161, v91, v217
	s_waitcnt lgkmcnt(4)
	ds_read_b128 v[46:49], v219 offset:12976
	ds_read_b128 v[50:53], v219 offset:12992
	v_fma_f32 v214, -v162, v92, v214
	v_fma_f32 v215, -v163, v93, v215
	v_fma_f32 v216, -v164, v94, v216
	v_fma_f32 v217, -v165, v95, v217
	v_fma_f32 v214, -v166, v96, v214
	v_fma_f32 v215, -v167, v97, v215
	v_fma_f32 v216, -v168, v98, v216
	v_fma_f32 v217, -v169, v99, v217
	v_fma_f32 v214, -v170, v100, v214
	v_fma_f32 v215, -v171, v101, v215
	v_fma_f32 v216, -v172, v102, v216
	v_fma_f32 v217, -v173, v103, v217
	v_fma_f32 v214, -v174, v108, v214
	v_fma_f32 v215, -v175, v109, v215
	v_fma_f32 v216, -v176, v110, v216
	v_fma_f32 v217, -v177, v111, v217
	v_fma_f32 v214, -v178, v112, v214
	v_fma_f32 v215, -v179, v113, v215
	v_fma_f32 v216, -v180, v114, v216
	v_fma_f32 v217, -v181, v115, v217
	v_fma_f32 v214, -v182, v116, v214
	v_fma_f32 v215, -v183, v117, v215
	v_fma_f32 v216, -v184, v118, v216
	v_fma_f32 v217, -v185, v119, v217
	v_fma_f32 v214, -v186, v120, v214
	v_add_f32_e32 v214, v215, v214
	v_add_f32_e32 v215, v216, v217
	v_add_f32_e32 v187, v215, v214
	ds_write_b32 v218, v187 offset:50960
	s_waitcnt lgkmcnt(0)
	ds_read_b32 v213, v218 offset:53040
	ds_read_b128 v[68:71], v219 offset:13056
	ds_read_b128 v[72:75], v219 offset:13072
	ds_read_b128 v[76:79], v219 offset:13088
	ds_read_b128 v[80:83], v219 offset:13104
	ds_read_b128 v[84:87], v219 offset:13120
	ds_read_b128 v[88:91], v219 offset:13136
	ds_read_b128 v[92:95], v219 offset:13152
	ds_read_b128 v[96:99], v219 offset:13168
	ds_read_b128 v[100:103], v219 offset:13184
	ds_read_b128 v[108:111], v219 offset:13200
	ds_read_b128 v[112:115], v219 offset:13216
	v_fma_f32 v214, -v138, v0, v212
	v_fma_f32 v215, -v139, v1, 0
	v_fma_f32 v216, -v140, v2, 0
	v_fma_f32 v217, -v141, v3, 0
	v_fma_f32 v214, -v142, v4, v214
	v_fma_f32 v215, -v143, v5, v215
	v_fma_f32 v216, -v144, v6, v216
	v_fma_f32 v217, -v145, v7, v217
	v_fma_f32 v214, -v146, v8, v214
	v_fma_f32 v215, -v147, v9, v215
	v_fma_f32 v216, -v148, v10, v216
	v_fma_f32 v217, -v149, v11, v217
	v_fma_f32 v214, -v150, v12, v214
	v_fma_f32 v215, -v151, v13, v215
	v_fma_f32 v216, -v152, v14, v216
	v_fma_f32 v217, -v153, v15, v217
	v_fma_f32 v214, -v154, v18, v214
	v_fma_f32 v215, -v155, v19, v215
	v_fma_f32 v216, -v156, v20, v216
	v_fma_f32 v217, -v157, v21, v217
	v_fma_f32 v214, -v158, v22, v214
	v_fma_f32 v215, -v159, v23, v215
	v_fma_f32 v216, -v160, v24, v216
	v_fma_f32 v217, -v161, v25, v217
	s_waitcnt lgkmcnt(4)
	ds_read_b128 v[116:119], v219 offset:13232
	ds_read_b128 v[120:123], v219 offset:13248
	v_fma_f32 v214, -v162, v26, v214
	v_fma_f32 v215, -v163, v27, v215
	v_fma_f32 v216, -v164, v28, v216
	v_fma_f32 v217, -v165, v29, v217
	v_fma_f32 v214, -v166, v30, v214
	v_fma_f32 v215, -v167, v31, v215
	v_fma_f32 v216, -v168, v32, v216
	v_fma_f32 v217, -v169, v33, v217
	v_fma_f32 v214, -v170, v34, v214
	v_fma_f32 v215, -v171, v35, v215
	v_fma_f32 v216, -v172, v36, v216
	v_fma_f32 v217, -v173, v37, v217
	v_fma_f32 v214, -v174, v38, v214
	v_fma_f32 v215, -v175, v39, v215
	v_fma_f32 v216, -v176, v40, v216
	v_fma_f32 v217, -v177, v41, v217
	v_fma_f32 v214, -v178, v42, v214
	v_fma_f32 v215, -v179, v43, v215
	v_fma_f32 v216, -v180, v44, v216
	v_fma_f32 v217, -v181, v45, v217
	v_fma_f32 v214, -v182, v46, v214
	v_fma_f32 v215, -v183, v47, v215
	v_fma_f32 v216, -v184, v48, v216
	v_fma_f32 v217, -v185, v49, v217
	v_fma_f32 v214, -v186, v50, v214
	v_fma_f32 v215, -v187, v51, v215
	v_add_f32_e32 v214, v215, v214
	v_add_f32_e32 v215, v216, v217
	v_add_f32_e32 v188, v215, v214
	ds_write_b32 v218, v188 offset:52000
	s_waitcnt lgkmcnt(0)
	ds_read_b32 v212, v218 offset:54080
	ds_read_b128 v[0:3], v219 offset:13312
	ds_read_b128 v[4:7], v219 offset:13328
	ds_read_b128 v[8:11], v219 offset:13344
	ds_read_b128 v[12:15], v219 offset:13360
	ds_read_b128 v[18:21], v219 offset:13376
	ds_read_b128 v[22:25], v219 offset:13392
	ds_read_b128 v[26:29], v219 offset:13408
	ds_read_b128 v[30:33], v219 offset:13424
	ds_read_b128 v[34:37], v219 offset:13440
	ds_read_b128 v[38:41], v219 offset:13456
	ds_read_b128 v[42:45], v219 offset:13472
	v_fma_f32 v214, -v138, v68, v213
	v_fma_f32 v215, -v139, v69, 0
	v_fma_f32 v216, -v140, v70, 0
	v_fma_f32 v217, -v141, v71, 0
	v_fma_f32 v214, -v142, v72, v214
	v_fma_f32 v215, -v143, v73, v215
	v_fma_f32 v216, -v144, v74, v216
	v_fma_f32 v217, -v145, v75, v217
	v_fma_f32 v214, -v146, v76, v214
	v_fma_f32 v215, -v147, v77, v215
	v_fma_f32 v216, -v148, v78, v216
	v_fma_f32 v217, -v149, v79, v217
	v_fma_f32 v214, -v150, v80, v214
	v_fma_f32 v215, -v151, v81, v215
	v_fma_f32 v216, -v152, v82, v216
	v_fma_f32 v217, -v153, v83, v217
	v_fma_f32 v214, -v154, v84, v214
	v_fma_f32 v215, -v155, v85, v215
	v_fma_f32 v216, -v156, v86, v216
	v_fma_f32 v217, -v157, v87, v217
	v_fma_f32 v214, -v158, v88, v214
	v_fma_f32 v215, -v159, v89, v215
	v_fma_f32 v216, -v160, v90, v216
	v_fma_f32 v217, -v161, v91, v217
	s_waitcnt lgkmcnt(4)
	ds_read_b128 v[46:49], v219 offset:13488
	ds_read_b128 v[50:53], v219 offset:13504
	v_fma_f32 v214, -v162, v92, v214
	v_fma_f32 v215, -v163, v93, v215
	v_fma_f32 v216, -v164, v94, v216
	v_fma_f32 v217, -v165, v95, v217
	v_fma_f32 v214, -v166, v96, v214
	v_fma_f32 v215, -v167, v97, v215
	v_fma_f32 v216, -v168, v98, v216
	v_fma_f32 v217, -v169, v99, v217
	v_fma_f32 v214, -v170, v100, v214
	v_fma_f32 v215, -v171, v101, v215
	v_fma_f32 v216, -v172, v102, v216
	v_fma_f32 v217, -v173, v103, v217
	v_fma_f32 v214, -v174, v108, v214
	v_fma_f32 v215, -v175, v109, v215
	v_fma_f32 v216, -v176, v110, v216
	v_fma_f32 v217, -v177, v111, v217
	v_fma_f32 v214, -v178, v112, v214
	v_fma_f32 v215, -v179, v113, v215
	v_fma_f32 v216, -v180, v114, v216
	v_fma_f32 v217, -v181, v115, v217
	v_fma_f32 v214, -v182, v116, v214
	v_fma_f32 v215, -v183, v117, v215
	v_fma_f32 v216, -v184, v118, v216
	v_fma_f32 v217, -v185, v119, v217
	v_fma_f32 v214, -v186, v120, v214
	v_fma_f32 v215, -v187, v121, v215
	v_fma_f32 v216, -v188, v122, v216
	v_add_f32_e32 v214, v215, v214
	v_add_f32_e32 v215, v216, v217
	v_add_f32_e32 v189, v215, v214
	ds_write_b32 v218, v189 offset:53040
	s_waitcnt lgkmcnt(0)
	ds_read_b32 v213, v218 offset:55120
	ds_read_b128 v[68:71], v219 offset:13568
	ds_read_b128 v[72:75], v219 offset:13584
	ds_read_b128 v[76:79], v219 offset:13600
	ds_read_b128 v[80:83], v219 offset:13616
	ds_read_b128 v[84:87], v219 offset:13632
	ds_read_b128 v[88:91], v219 offset:13648
	ds_read_b128 v[92:95], v219 offset:13664
	ds_read_b128 v[96:99], v219 offset:13680
	ds_read_b128 v[100:103], v219 offset:13696
	ds_read_b128 v[108:111], v219 offset:13712
	ds_read_b128 v[112:115], v219 offset:13728
	v_fma_f32 v214, -v138, v0, v212
	v_fma_f32 v215, -v139, v1, 0
	v_fma_f32 v216, -v140, v2, 0
	v_fma_f32 v217, -v141, v3, 0
	v_fma_f32 v214, -v142, v4, v214
	v_fma_f32 v215, -v143, v5, v215
	v_fma_f32 v216, -v144, v6, v216
	v_fma_f32 v217, -v145, v7, v217
	v_fma_f32 v214, -v146, v8, v214
	v_fma_f32 v215, -v147, v9, v215
	v_fma_f32 v216, -v148, v10, v216
	v_fma_f32 v217, -v149, v11, v217
	v_fma_f32 v214, -v150, v12, v214
	v_fma_f32 v215, -v151, v13, v215
	v_fma_f32 v216, -v152, v14, v216
	v_fma_f32 v217, -v153, v15, v217
	v_fma_f32 v214, -v154, v18, v214
	v_fma_f32 v215, -v155, v19, v215
	v_fma_f32 v216, -v156, v20, v216
	v_fma_f32 v217, -v157, v21, v217
	v_fma_f32 v214, -v158, v22, v214
	v_fma_f32 v215, -v159, v23, v215
	v_fma_f32 v216, -v160, v24, v216
	v_fma_f32 v217, -v161, v25, v217
	s_waitcnt lgkmcnt(4)
	ds_read_b128 v[116:119], v219 offset:13744
	ds_read_b128 v[120:123], v219 offset:13760
	ds_read_b128 v[124:127], v219 offset:13776
	v_fma_f32 v214, -v162, v26, v214
	v_fma_f32 v215, -v163, v27, v215
	v_fma_f32 v216, -v164, v28, v216
	v_fma_f32 v217, -v165, v29, v217
	v_fma_f32 v214, -v166, v30, v214
	v_fma_f32 v215, -v167, v31, v215
	v_fma_f32 v216, -v168, v32, v216
	v_fma_f32 v217, -v169, v33, v217
	v_fma_f32 v214, -v170, v34, v214
	v_fma_f32 v215, -v171, v35, v215
	v_fma_f32 v216, -v172, v36, v216
	v_fma_f32 v217, -v173, v37, v217
	v_fma_f32 v214, -v174, v38, v214
	v_fma_f32 v215, -v175, v39, v215
	v_fma_f32 v216, -v176, v40, v216
	v_fma_f32 v217, -v177, v41, v217
	v_fma_f32 v214, -v178, v42, v214
	v_fma_f32 v215, -v179, v43, v215
	v_fma_f32 v216, -v180, v44, v216
	v_fma_f32 v217, -v181, v45, v217
	v_fma_f32 v214, -v182, v46, v214
	v_fma_f32 v215, -v183, v47, v215
	v_fma_f32 v216, -v184, v48, v216
	v_fma_f32 v217, -v185, v49, v217
	v_fma_f32 v214, -v186, v50, v214
	v_fma_f32 v215, -v187, v51, v215
	v_fma_f32 v216, -v188, v52, v216
	v_fma_f32 v217, -v189, v53, v217
	v_add_f32_e32 v214, v215, v214
	v_add_f32_e32 v215, v216, v217
	v_add_f32_e32 v190, v215, v214
	ds_write_b32 v218, v190 offset:54080
	s_waitcnt lgkmcnt(0)
	ds_read_b32 v212, v218 offset:56160
	ds_read_b128 v[0:3], v219 offset:13824
	ds_read_b128 v[4:7], v219 offset:13840
	ds_read_b128 v[8:11], v219 offset:13856
	ds_read_b128 v[12:15], v219 offset:13872
	ds_read_b128 v[18:21], v219 offset:13888
	ds_read_b128 v[22:25], v219 offset:13904
	ds_read_b128 v[26:29], v219 offset:13920
	ds_read_b128 v[30:33], v219 offset:13936
	ds_read_b128 v[34:37], v219 offset:13952
	ds_read_b128 v[38:41], v219 offset:13968
	ds_read_b128 v[42:45], v219 offset:13984
	v_fma_f32 v214, -v138, v68, v213
	v_fma_f32 v215, -v139, v69, 0
	v_fma_f32 v216, -v140, v70, 0
	v_fma_f32 v217, -v141, v71, 0
	v_fma_f32 v214, -v142, v72, v214
	v_fma_f32 v215, -v143, v73, v215
	v_fma_f32 v216, -v144, v74, v216
	v_fma_f32 v217, -v145, v75, v217
	v_fma_f32 v214, -v146, v76, v214
	v_fma_f32 v215, -v147, v77, v215
	v_fma_f32 v216, -v148, v78, v216
	v_fma_f32 v217, -v149, v79, v217
	v_fma_f32 v214, -v150, v80, v214
	v_fma_f32 v215, -v151, v81, v215
	v_fma_f32 v216, -v152, v82, v216
	v_fma_f32 v217, -v153, v83, v217
	v_fma_f32 v214, -v154, v84, v214
	v_fma_f32 v215, -v155, v85, v215
	v_fma_f32 v216, -v156, v86, v216
	v_fma_f32 v217, -v157, v87, v217
	v_fma_f32 v214, -v158, v88, v214
	v_fma_f32 v215, -v159, v89, v215
	v_fma_f32 v216, -v160, v90, v216
	v_fma_f32 v217, -v161, v91, v217
	s_waitcnt lgkmcnt(4)
	ds_read_b128 v[46:49], v219 offset:14000
	ds_read_b128 v[50:53], v219 offset:14016
	ds_read_b128 v[54:57], v219 offset:14032
	v_fma_f32 v214, -v162, v92, v214
	v_fma_f32 v215, -v163, v93, v215
	v_fma_f32 v216, -v164, v94, v216
	v_fma_f32 v217, -v165, v95, v217
	v_fma_f32 v214, -v166, v96, v214
	v_fma_f32 v215, -v167, v97, v215
	v_fma_f32 v216, -v168, v98, v216
	v_fma_f32 v217, -v169, v99, v217
	v_fma_f32 v214, -v170, v100, v214
	v_fma_f32 v215, -v171, v101, v215
	v_fma_f32 v216, -v172, v102, v216
	v_fma_f32 v217, -v173, v103, v217
	v_fma_f32 v214, -v174, v108, v214
	v_fma_f32 v215, -v175, v109, v215
	v_fma_f32 v216, -v176, v110, v216
	v_fma_f32 v217, -v177, v111, v217
	v_fma_f32 v214, -v178, v112, v214
	v_fma_f32 v215, -v179, v113, v215
	v_fma_f32 v216, -v180, v114, v216
	v_fma_f32 v217, -v181, v115, v217
	v_fma_f32 v214, -v182, v116, v214
	v_fma_f32 v215, -v183, v117, v215
	v_fma_f32 v216, -v184, v118, v216
	v_fma_f32 v217, -v185, v119, v217
	v_fma_f32 v214, -v186, v120, v214
	v_fma_f32 v215, -v187, v121, v215
	v_fma_f32 v216, -v188, v122, v216
	v_fma_f32 v217, -v189, v123, v217
	v_fma_f32 v214, -v190, v124, v214
	v_add_f32_e32 v214, v215, v214
	v_add_f32_e32 v215, v216, v217
	v_add_f32_e32 v191, v215, v214
	ds_write_b32 v218, v191 offset:55120
	s_waitcnt lgkmcnt(0)
	ds_read_b32 v213, v218 offset:57200
	ds_read_b128 v[68:71], v219 offset:14080
	ds_read_b128 v[72:75], v219 offset:14096
	ds_read_b128 v[76:79], v219 offset:14112
	ds_read_b128 v[80:83], v219 offset:14128
	ds_read_b128 v[84:87], v219 offset:14144
	ds_read_b128 v[88:91], v219 offset:14160
	ds_read_b128 v[92:95], v219 offset:14176
	ds_read_b128 v[96:99], v219 offset:14192
	ds_read_b128 v[100:103], v219 offset:14208
	ds_read_b128 v[108:111], v219 offset:14224
	ds_read_b128 v[112:115], v219 offset:14240
	v_fma_f32 v214, -v138, v0, v212
	v_fma_f32 v215, -v139, v1, 0
	v_fma_f32 v216, -v140, v2, 0
	v_fma_f32 v217, -v141, v3, 0
	v_fma_f32 v214, -v142, v4, v214
	v_fma_f32 v215, -v143, v5, v215
	v_fma_f32 v216, -v144, v6, v216
	v_fma_f32 v217, -v145, v7, v217
	v_fma_f32 v214, -v146, v8, v214
	v_fma_f32 v215, -v147, v9, v215
	v_fma_f32 v216, -v148, v10, v216
	v_fma_f32 v217, -v149, v11, v217
	v_fma_f32 v214, -v150, v12, v214
	v_fma_f32 v215, -v151, v13, v215
	v_fma_f32 v216, -v152, v14, v216
	v_fma_f32 v217, -v153, v15, v217
	v_fma_f32 v214, -v154, v18, v214
	v_fma_f32 v215, -v155, v19, v215
	v_fma_f32 v216, -v156, v20, v216
	v_fma_f32 v217, -v157, v21, v217
	v_fma_f32 v214, -v158, v22, v214
	v_fma_f32 v215, -v159, v23, v215
	v_fma_f32 v216, -v160, v24, v216
	v_fma_f32 v217, -v161, v25, v217
	s_waitcnt lgkmcnt(4)
	ds_read_b128 v[116:119], v219 offset:14256
	ds_read_b128 v[120:123], v219 offset:14272
	ds_read_b128 v[124:127], v219 offset:14288
	v_fma_f32 v214, -v162, v26, v214
	v_fma_f32 v215, -v163, v27, v215
	v_fma_f32 v216, -v164, v28, v216
	v_fma_f32 v217, -v165, v29, v217
	v_fma_f32 v214, -v166, v30, v214
	v_fma_f32 v215, -v167, v31, v215
	v_fma_f32 v216, -v168, v32, v216
	v_fma_f32 v217, -v169, v33, v217
	v_fma_f32 v214, -v170, v34, v214
	v_fma_f32 v215, -v171, v35, v215
	v_fma_f32 v216, -v172, v36, v216
	v_fma_f32 v217, -v173, v37, v217
	v_fma_f32 v214, -v174, v38, v214
	v_fma_f32 v215, -v175, v39, v215
	v_fma_f32 v216, -v176, v40, v216
	v_fma_f32 v217, -v177, v41, v217
	v_fma_f32 v214, -v178, v42, v214
	v_fma_f32 v215, -v179, v43, v215
	v_fma_f32 v216, -v180, v44, v216
	v_fma_f32 v217, -v181, v45, v217
	v_fma_f32 v214, -v182, v46, v214
	v_fma_f32 v215, -v183, v47, v215
	v_fma_f32 v216, -v184, v48, v216
	v_fma_f32 v217, -v185, v49, v217
	v_fma_f32 v214, -v186, v50, v214
	v_fma_f32 v215, -v187, v51, v215
	v_fma_f32 v216, -v188, v52, v216
	v_fma_f32 v217, -v189, v53, v217
	v_fma_f32 v214, -v190, v54, v214
	v_fma_f32 v215, -v191, v55, v215
	v_add_f32_e32 v214, v215, v214
	v_add_f32_e32 v215, v216, v217
	v_add_f32_e32 v192, v215, v214
	ds_write_b32 v218, v192 offset:56160
	s_waitcnt lgkmcnt(0)
	ds_read_b32 v212, v218 offset:58240
	ds_read_b128 v[0:3], v219 offset:14336
	ds_read_b128 v[4:7], v219 offset:14352
	ds_read_b128 v[8:11], v219 offset:14368
	ds_read_b128 v[12:15], v219 offset:14384
	ds_read_b128 v[18:21], v219 offset:14400
	ds_read_b128 v[22:25], v219 offset:14416
	ds_read_b128 v[26:29], v219 offset:14432
	ds_read_b128 v[30:33], v219 offset:14448
	ds_read_b128 v[34:37], v219 offset:14464
	ds_read_b128 v[38:41], v219 offset:14480
	ds_read_b128 v[42:45], v219 offset:14496
	v_fma_f32 v214, -v138, v68, v213
	v_fma_f32 v215, -v139, v69, 0
	v_fma_f32 v216, -v140, v70, 0
	v_fma_f32 v217, -v141, v71, 0
	v_fma_f32 v214, -v142, v72, v214
	v_fma_f32 v215, -v143, v73, v215
	v_fma_f32 v216, -v144, v74, v216
	v_fma_f32 v217, -v145, v75, v217
	v_fma_f32 v214, -v146, v76, v214
	v_fma_f32 v215, -v147, v77, v215
	v_fma_f32 v216, -v148, v78, v216
	v_fma_f32 v217, -v149, v79, v217
	v_fma_f32 v214, -v150, v80, v214
	v_fma_f32 v215, -v151, v81, v215
	v_fma_f32 v216, -v152, v82, v216
	v_fma_f32 v217, -v153, v83, v217
	v_fma_f32 v214, -v154, v84, v214
	v_fma_f32 v215, -v155, v85, v215
	v_fma_f32 v216, -v156, v86, v216
	v_fma_f32 v217, -v157, v87, v217
	v_fma_f32 v214, -v158, v88, v214
	v_fma_f32 v215, -v159, v89, v215
	v_fma_f32 v216, -v160, v90, v216
	v_fma_f32 v217, -v161, v91, v217
	s_waitcnt lgkmcnt(4)
	ds_read_b128 v[46:49], v219 offset:14512
	ds_read_b128 v[50:53], v219 offset:14528
	ds_read_b128 v[54:57], v219 offset:14544
	v_fma_f32 v214, -v162, v92, v214
	v_fma_f32 v215, -v163, v93, v215
	v_fma_f32 v216, -v164, v94, v216
	v_fma_f32 v217, -v165, v95, v217
	v_fma_f32 v214, -v166, v96, v214
	v_fma_f32 v215, -v167, v97, v215
	v_fma_f32 v216, -v168, v98, v216
	v_fma_f32 v217, -v169, v99, v217
	v_fma_f32 v214, -v170, v100, v214
	v_fma_f32 v215, -v171, v101, v215
	v_fma_f32 v216, -v172, v102, v216
	v_fma_f32 v217, -v173, v103, v217
	v_fma_f32 v214, -v174, v108, v214
	v_fma_f32 v215, -v175, v109, v215
	v_fma_f32 v216, -v176, v110, v216
	v_fma_f32 v217, -v177, v111, v217
	v_fma_f32 v214, -v178, v112, v214
	v_fma_f32 v215, -v179, v113, v215
	v_fma_f32 v216, -v180, v114, v216
	v_fma_f32 v217, -v181, v115, v217
	v_fma_f32 v214, -v182, v116, v214
	v_fma_f32 v215, -v183, v117, v215
	v_fma_f32 v216, -v184, v118, v216
	v_fma_f32 v217, -v185, v119, v217
	v_fma_f32 v214, -v186, v120, v214
	v_fma_f32 v215, -v187, v121, v215
	v_fma_f32 v216, -v188, v122, v216
	v_fma_f32 v217, -v189, v123, v217
	v_fma_f32 v214, -v190, v124, v214
	v_fma_f32 v215, -v191, v125, v215
	v_fma_f32 v216, -v192, v126, v216
	v_add_f32_e32 v214, v215, v214
	v_add_f32_e32 v215, v216, v217
	v_add_f32_e32 v193, v215, v214
	ds_write_b32 v218, v193 offset:57200
	s_waitcnt lgkmcnt(0)
	ds_read_b32 v213, v218 offset:59280
	ds_read_b128 v[68:71], v219 offset:14592
	ds_read_b128 v[72:75], v219 offset:14608
	ds_read_b128 v[76:79], v219 offset:14624
	ds_read_b128 v[80:83], v219 offset:14640
	ds_read_b128 v[84:87], v219 offset:14656
	ds_read_b128 v[88:91], v219 offset:14672
	ds_read_b128 v[92:95], v219 offset:14688
	ds_read_b128 v[96:99], v219 offset:14704
	ds_read_b128 v[100:103], v219 offset:14720
	ds_read_b128 v[108:111], v219 offset:14736
	ds_read_b128 v[112:115], v219 offset:14752
	v_fma_f32 v214, -v138, v0, v212
	v_fma_f32 v215, -v139, v1, 0
	v_fma_f32 v216, -v140, v2, 0
	v_fma_f32 v217, -v141, v3, 0
	v_fma_f32 v214, -v142, v4, v214
	v_fma_f32 v215, -v143, v5, v215
	v_fma_f32 v216, -v144, v6, v216
	v_fma_f32 v217, -v145, v7, v217
	v_fma_f32 v214, -v146, v8, v214
	v_fma_f32 v215, -v147, v9, v215
	v_fma_f32 v216, -v148, v10, v216
	v_fma_f32 v217, -v149, v11, v217
	v_fma_f32 v214, -v150, v12, v214
	v_fma_f32 v215, -v151, v13, v215
	v_fma_f32 v216, -v152, v14, v216
	v_fma_f32 v217, -v153, v15, v217
	v_fma_f32 v214, -v154, v18, v214
	v_fma_f32 v215, -v155, v19, v215
	v_fma_f32 v216, -v156, v20, v216
	v_fma_f32 v217, -v157, v21, v217
	v_fma_f32 v214, -v158, v22, v214
	v_fma_f32 v215, -v159, v23, v215
	v_fma_f32 v216, -v160, v24, v216
	v_fma_f32 v217, -v161, v25, v217
	s_waitcnt lgkmcnt(4)
	ds_read_b128 v[116:119], v219 offset:14768
	ds_read_b128 v[120:123], v219 offset:14784
	ds_read_b128 v[124:127], v219 offset:14800
	ds_read_b128 v[128:131], v219 offset:14816
	v_fma_f32 v214, -v162, v26, v214
	v_fma_f32 v215, -v163, v27, v215
	v_fma_f32 v216, -v164, v28, v216
	v_fma_f32 v217, -v165, v29, v217
	v_fma_f32 v214, -v166, v30, v214
	v_fma_f32 v215, -v167, v31, v215
	v_fma_f32 v216, -v168, v32, v216
	v_fma_f32 v217, -v169, v33, v217
	v_fma_f32 v214, -v170, v34, v214
	v_fma_f32 v215, -v171, v35, v215
	v_fma_f32 v216, -v172, v36, v216
	v_fma_f32 v217, -v173, v37, v217
	v_fma_f32 v214, -v174, v38, v214
	v_fma_f32 v215, -v175, v39, v215
	v_fma_f32 v216, -v176, v40, v216
	v_fma_f32 v217, -v177, v41, v217
	v_fma_f32 v214, -v178, v42, v214
	v_fma_f32 v215, -v179, v43, v215
	v_fma_f32 v216, -v180, v44, v216
	v_fma_f32 v217, -v181, v45, v217
	v_fma_f32 v214, -v182, v46, v214
	v_fma_f32 v215, -v183, v47, v215
	v_fma_f32 v216, -v184, v48, v216
	v_fma_f32 v217, -v185, v49, v217
	v_fma_f32 v214, -v186, v50, v214
	v_fma_f32 v215, -v187, v51, v215
	v_fma_f32 v216, -v188, v52, v216
	v_fma_f32 v217, -v189, v53, v217
	v_fma_f32 v214, -v190, v54, v214
	v_fma_f32 v215, -v191, v55, v215
	v_fma_f32 v216, -v192, v56, v216
	v_fma_f32 v217, -v193, v57, v217
	v_add_f32_e32 v214, v215, v214
	v_add_f32_e32 v215, v216, v217
	v_add_f32_e32 v194, v215, v214
	ds_write_b32 v218, v194 offset:58240
	s_waitcnt lgkmcnt(0)
	ds_read_b32 v212, v218 offset:60320
	ds_read_b128 v[0:3], v219 offset:14848
	ds_read_b128 v[4:7], v219 offset:14864
	ds_read_b128 v[8:11], v219 offset:14880
	ds_read_b128 v[12:15], v219 offset:14896
	ds_read_b128 v[18:21], v219 offset:14912
	ds_read_b128 v[22:25], v219 offset:14928
	ds_read_b128 v[26:29], v219 offset:14944
	ds_read_b128 v[30:33], v219 offset:14960
	ds_read_b128 v[34:37], v219 offset:14976
	ds_read_b128 v[38:41], v219 offset:14992
	ds_read_b128 v[42:45], v219 offset:15008
	v_fma_f32 v214, -v138, v68, v213
	v_fma_f32 v215, -v139, v69, 0
	v_fma_f32 v216, -v140, v70, 0
	v_fma_f32 v217, -v141, v71, 0
	v_fma_f32 v214, -v142, v72, v214
	v_fma_f32 v215, -v143, v73, v215
	v_fma_f32 v216, -v144, v74, v216
	v_fma_f32 v217, -v145, v75, v217
	v_fma_f32 v214, -v146, v76, v214
	v_fma_f32 v215, -v147, v77, v215
	v_fma_f32 v216, -v148, v78, v216
	v_fma_f32 v217, -v149, v79, v217
	v_fma_f32 v214, -v150, v80, v214
	v_fma_f32 v215, -v151, v81, v215
	v_fma_f32 v216, -v152, v82, v216
	v_fma_f32 v217, -v153, v83, v217
	v_fma_f32 v214, -v154, v84, v214
	v_fma_f32 v215, -v155, v85, v215
	v_fma_f32 v216, -v156, v86, v216
	v_fma_f32 v217, -v157, v87, v217
	v_fma_f32 v214, -v158, v88, v214
	v_fma_f32 v215, -v159, v89, v215
	v_fma_f32 v216, -v160, v90, v216
	v_fma_f32 v217, -v161, v91, v217
	s_waitcnt lgkmcnt(4)
	ds_read_b128 v[46:49], v219 offset:15024
	ds_read_b128 v[50:53], v219 offset:15040
	ds_read_b128 v[54:57], v219 offset:15056
	ds_read_b128 v[58:61], v219 offset:15072
	v_fma_f32 v214, -v162, v92, v214
	v_fma_f32 v215, -v163, v93, v215
	v_fma_f32 v216, -v164, v94, v216
	v_fma_f32 v217, -v165, v95, v217
	v_fma_f32 v214, -v166, v96, v214
	v_fma_f32 v215, -v167, v97, v215
	v_fma_f32 v216, -v168, v98, v216
	v_fma_f32 v217, -v169, v99, v217
	v_fma_f32 v214, -v170, v100, v214
	v_fma_f32 v215, -v171, v101, v215
	v_fma_f32 v216, -v172, v102, v216
	v_fma_f32 v217, -v173, v103, v217
	v_fma_f32 v214, -v174, v108, v214
	v_fma_f32 v215, -v175, v109, v215
	v_fma_f32 v216, -v176, v110, v216
	v_fma_f32 v217, -v177, v111, v217
	v_fma_f32 v214, -v178, v112, v214
	v_fma_f32 v215, -v179, v113, v215
	v_fma_f32 v216, -v180, v114, v216
	v_fma_f32 v217, -v181, v115, v217
	v_fma_f32 v214, -v182, v116, v214
	v_fma_f32 v215, -v183, v117, v215
	v_fma_f32 v216, -v184, v118, v216
	v_fma_f32 v217, -v185, v119, v217
	v_fma_f32 v214, -v186, v120, v214
	v_fma_f32 v215, -v187, v121, v215
	v_fma_f32 v216, -v188, v122, v216
	v_fma_f32 v217, -v189, v123, v217
	v_fma_f32 v214, -v190, v124, v214
	v_fma_f32 v215, -v191, v125, v215
	v_fma_f32 v216, -v192, v126, v216
	v_fma_f32 v217, -v193, v127, v217
	v_fma_f32 v214, -v194, v128, v214
	v_add_f32_e32 v214, v215, v214
	v_add_f32_e32 v215, v216, v217
	v_add_f32_e32 v195, v215, v214
	ds_write_b32 v218, v195 offset:59280
	s_waitcnt lgkmcnt(0)
	ds_read_b32 v213, v218 offset:61360
	ds_read_b128 v[68:71], v219 offset:15104
	ds_read_b128 v[72:75], v219 offset:15120
	ds_read_b128 v[76:79], v219 offset:15136
	ds_read_b128 v[80:83], v219 offset:15152
	ds_read_b128 v[84:87], v219 offset:15168
	ds_read_b128 v[88:91], v219 offset:15184
	ds_read_b128 v[92:95], v219 offset:15200
	ds_read_b128 v[96:99], v219 offset:15216
	ds_read_b128 v[100:103], v219 offset:15232
	ds_read_b128 v[108:111], v219 offset:15248
	ds_read_b128 v[112:115], v219 offset:15264
	v_fma_f32 v214, -v138, v0, v212
	v_fma_f32 v215, -v139, v1, 0
	v_fma_f32 v216, -v140, v2, 0
	v_fma_f32 v217, -v141, v3, 0
	v_fma_f32 v214, -v142, v4, v214
	v_fma_f32 v215, -v143, v5, v215
	v_fma_f32 v216, -v144, v6, v216
	v_fma_f32 v217, -v145, v7, v217
	v_fma_f32 v214, -v146, v8, v214
	v_fma_f32 v215, -v147, v9, v215
	v_fma_f32 v216, -v148, v10, v216
	v_fma_f32 v217, -v149, v11, v217
	v_fma_f32 v214, -v150, v12, v214
	v_fma_f32 v215, -v151, v13, v215
	v_fma_f32 v216, -v152, v14, v216
	v_fma_f32 v217, -v153, v15, v217
	v_fma_f32 v214, -v154, v18, v214
	v_fma_f32 v215, -v155, v19, v215
	v_fma_f32 v216, -v156, v20, v216
	v_fma_f32 v217, -v157, v21, v217
	v_fma_f32 v214, -v158, v22, v214
	v_fma_f32 v215, -v159, v23, v215
	v_fma_f32 v216, -v160, v24, v216
	v_fma_f32 v217, -v161, v25, v217
	s_waitcnt lgkmcnt(4)
	ds_read_b128 v[116:119], v219 offset:15280
	ds_read_b128 v[120:123], v219 offset:15296
	ds_read_b128 v[124:127], v219 offset:15312
	ds_read_b128 v[128:131], v219 offset:15328
	v_fma_f32 v214, -v162, v26, v214
	v_fma_f32 v215, -v163, v27, v215
	v_fma_f32 v216, -v164, v28, v216
	v_fma_f32 v217, -v165, v29, v217
	v_fma_f32 v214, -v166, v30, v214
	v_fma_f32 v215, -v167, v31, v215
	v_fma_f32 v216, -v168, v32, v216
	v_fma_f32 v217, -v169, v33, v217
	v_fma_f32 v214, -v170, v34, v214
	v_fma_f32 v215, -v171, v35, v215
	v_fma_f32 v216, -v172, v36, v216
	v_fma_f32 v217, -v173, v37, v217
	v_fma_f32 v214, -v174, v38, v214
	v_fma_f32 v215, -v175, v39, v215
	v_fma_f32 v216, -v176, v40, v216
	v_fma_f32 v217, -v177, v41, v217
	v_fma_f32 v214, -v178, v42, v214
	v_fma_f32 v215, -v179, v43, v215
	v_fma_f32 v216, -v180, v44, v216
	v_fma_f32 v217, -v181, v45, v217
	v_fma_f32 v214, -v182, v46, v214
	v_fma_f32 v215, -v183, v47, v215
	v_fma_f32 v216, -v184, v48, v216
	v_fma_f32 v217, -v185, v49, v217
	v_fma_f32 v214, -v186, v50, v214
	v_fma_f32 v215, -v187, v51, v215
	v_fma_f32 v216, -v188, v52, v216
	v_fma_f32 v217, -v189, v53, v217
	v_fma_f32 v214, -v190, v54, v214
	v_fma_f32 v215, -v191, v55, v215
	v_fma_f32 v216, -v192, v56, v216
	v_fma_f32 v217, -v193, v57, v217
	v_fma_f32 v214, -v194, v58, v214
	v_fma_f32 v215, -v195, v59, v215
	v_add_f32_e32 v214, v215, v214
	v_add_f32_e32 v215, v216, v217
	v_add_f32_e32 v196, v215, v214
	ds_write_b32 v218, v196 offset:60320
	s_waitcnt lgkmcnt(0)
	ds_read_b32 v212, v218 offset:62400
	ds_read_b128 v[0:3], v219 offset:15360
	ds_read_b128 v[4:7], v219 offset:15376
	ds_read_b128 v[8:11], v219 offset:15392
	ds_read_b128 v[12:15], v219 offset:15408
	ds_read_b128 v[18:21], v219 offset:15424
	ds_read_b128 v[22:25], v219 offset:15440
	ds_read_b128 v[26:29], v219 offset:15456
	ds_read_b128 v[30:33], v219 offset:15472
	ds_read_b128 v[34:37], v219 offset:15488
	ds_read_b128 v[38:41], v219 offset:15504
	ds_read_b128 v[42:45], v219 offset:15520
	v_fma_f32 v214, -v138, v68, v213
	v_fma_f32 v215, -v139, v69, 0
	v_fma_f32 v216, -v140, v70, 0
	v_fma_f32 v217, -v141, v71, 0
	v_fma_f32 v214, -v142, v72, v214
	v_fma_f32 v215, -v143, v73, v215
	v_fma_f32 v216, -v144, v74, v216
	v_fma_f32 v217, -v145, v75, v217
	v_fma_f32 v214, -v146, v76, v214
	v_fma_f32 v215, -v147, v77, v215
	v_fma_f32 v216, -v148, v78, v216
	v_fma_f32 v217, -v149, v79, v217
	v_fma_f32 v214, -v150, v80, v214
	v_fma_f32 v215, -v151, v81, v215
	v_fma_f32 v216, -v152, v82, v216
	v_fma_f32 v217, -v153, v83, v217
	v_fma_f32 v214, -v154, v84, v214
	v_fma_f32 v215, -v155, v85, v215
	v_fma_f32 v216, -v156, v86, v216
	v_fma_f32 v217, -v157, v87, v217
	v_fma_f32 v214, -v158, v88, v214
	v_fma_f32 v215, -v159, v89, v215
	v_fma_f32 v216, -v160, v90, v216
	v_fma_f32 v217, -v161, v91, v217
	s_waitcnt lgkmcnt(4)
	ds_read_b128 v[46:49], v219 offset:15536
	ds_read_b128 v[50:53], v219 offset:15552
	ds_read_b128 v[54:57], v219 offset:15568
	ds_read_b128 v[58:61], v219 offset:15584
	v_fma_f32 v214, -v162, v92, v214
	v_fma_f32 v215, -v163, v93, v215
	v_fma_f32 v216, -v164, v94, v216
	v_fma_f32 v217, -v165, v95, v217
	v_fma_f32 v214, -v166, v96, v214
	v_fma_f32 v215, -v167, v97, v215
	v_fma_f32 v216, -v168, v98, v216
	v_fma_f32 v217, -v169, v99, v217
	v_fma_f32 v214, -v170, v100, v214
	v_fma_f32 v215, -v171, v101, v215
	v_fma_f32 v216, -v172, v102, v216
	v_fma_f32 v217, -v173, v103, v217
	v_fma_f32 v214, -v174, v108, v214
	v_fma_f32 v215, -v175, v109, v215
	v_fma_f32 v216, -v176, v110, v216
	v_fma_f32 v217, -v177, v111, v217
	v_fma_f32 v214, -v178, v112, v214
	v_fma_f32 v215, -v179, v113, v215
	v_fma_f32 v216, -v180, v114, v216
	v_fma_f32 v217, -v181, v115, v217
	v_fma_f32 v214, -v182, v116, v214
	v_fma_f32 v215, -v183, v117, v215
	v_fma_f32 v216, -v184, v118, v216
	v_fma_f32 v217, -v185, v119, v217
	v_fma_f32 v214, -v186, v120, v214
	v_fma_f32 v215, -v187, v121, v215
	v_fma_f32 v216, -v188, v122, v216
	v_fma_f32 v217, -v189, v123, v217
	v_fma_f32 v214, -v190, v124, v214
	v_fma_f32 v215, -v191, v125, v215
	v_fma_f32 v216, -v192, v126, v216
	v_fma_f32 v217, -v193, v127, v217
	v_fma_f32 v214, -v194, v128, v214
	v_fma_f32 v215, -v195, v129, v215
	v_fma_f32 v216, -v196, v130, v216
	v_add_f32_e32 v214, v215, v214
	v_add_f32_e32 v215, v216, v217
	v_add_f32_e32 v197, v215, v214
	ds_write_b32 v218, v197 offset:61360
	s_waitcnt lgkmcnt(0)
	ds_read_b32 v213, v218 offset:63440
	ds_read_b128 v[68:71], v219 offset:15616
	ds_read_b128 v[72:75], v219 offset:15632
	ds_read_b128 v[76:79], v219 offset:15648
	ds_read_b128 v[80:83], v219 offset:15664
	ds_read_b128 v[84:87], v219 offset:15680
	ds_read_b128 v[88:91], v219 offset:15696
	ds_read_b128 v[92:95], v219 offset:15712
	ds_read_b128 v[96:99], v219 offset:15728
	ds_read_b128 v[100:103], v219 offset:15744
	ds_read_b128 v[108:111], v219 offset:15760
	ds_read_b128 v[112:115], v219 offset:15776
	v_fma_f32 v214, -v138, v0, v212
	v_fma_f32 v215, -v139, v1, 0
	v_fma_f32 v216, -v140, v2, 0
	v_fma_f32 v217, -v141, v3, 0
	v_fma_f32 v214, -v142, v4, v214
	v_fma_f32 v215, -v143, v5, v215
	v_fma_f32 v216, -v144, v6, v216
	v_fma_f32 v217, -v145, v7, v217
	v_fma_f32 v214, -v146, v8, v214
	v_fma_f32 v215, -v147, v9, v215
	v_fma_f32 v216, -v148, v10, v216
	v_fma_f32 v217, -v149, v11, v217
	v_fma_f32 v214, -v150, v12, v214
	v_fma_f32 v215, -v151, v13, v215
	v_fma_f32 v216, -v152, v14, v216
	v_fma_f32 v217, -v153, v15, v217
	v_fma_f32 v214, -v154, v18, v214
	v_fma_f32 v215, -v155, v19, v215
	v_fma_f32 v216, -v156, v20, v216
	v_fma_f32 v217, -v157, v21, v217
	v_fma_f32 v214, -v158, v22, v214
	v_fma_f32 v215, -v159, v23, v215
	v_fma_f32 v216, -v160, v24, v216
	v_fma_f32 v217, -v161, v25, v217
	s_waitcnt lgkmcnt(4)
	ds_read_b128 v[116:119], v219 offset:15792
	ds_read_b128 v[120:123], v219 offset:15808
	ds_read_b128 v[124:127], v219 offset:15824
	ds_read_b128 v[128:131], v219 offset:15840
	ds_read_b128 v[132:135], v219 offset:15856
	v_fma_f32 v214, -v162, v26, v214
	v_fma_f32 v215, -v163, v27, v215
	v_fma_f32 v216, -v164, v28, v216
	v_fma_f32 v217, -v165, v29, v217
	v_fma_f32 v214, -v166, v30, v214
	v_fma_f32 v215, -v167, v31, v215
	v_fma_f32 v216, -v168, v32, v216
	v_fma_f32 v217, -v169, v33, v217
	v_fma_f32 v214, -v170, v34, v214
	v_fma_f32 v215, -v171, v35, v215
	v_fma_f32 v216, -v172, v36, v216
	v_fma_f32 v217, -v173, v37, v217
	v_fma_f32 v214, -v174, v38, v214
	v_fma_f32 v215, -v175, v39, v215
	v_fma_f32 v216, -v176, v40, v216
	v_fma_f32 v217, -v177, v41, v217
	v_fma_f32 v214, -v178, v42, v214
	v_fma_f32 v215, -v179, v43, v215
	v_fma_f32 v216, -v180, v44, v216
	v_fma_f32 v217, -v181, v45, v217
	v_fma_f32 v214, -v182, v46, v214
	v_fma_f32 v215, -v183, v47, v215
	v_fma_f32 v216, -v184, v48, v216
	v_fma_f32 v217, -v185, v49, v217
	v_fma_f32 v214, -v186, v50, v214
	v_fma_f32 v215, -v187, v51, v215
	v_fma_f32 v216, -v188, v52, v216
	v_fma_f32 v217, -v189, v53, v217
	v_fma_f32 v214, -v190, v54, v214
	v_fma_f32 v215, -v191, v55, v215
	v_fma_f32 v216, -v192, v56, v216
	v_fma_f32 v217, -v193, v57, v217
	v_fma_f32 v214, -v194, v58, v214
	v_fma_f32 v215, -v195, v59, v215
	v_fma_f32 v216, -v196, v60, v216
	v_fma_f32 v217, -v197, v61, v217
	v_add_f32_e32 v214, v215, v214
	v_add_f32_e32 v215, v216, v217
	v_add_f32_e32 v208, v215, v214
	ds_write_b32 v218, v208 offset:62400
	s_waitcnt lgkmcnt(0)
	ds_read_b32 v212, v218 offset:64480
	ds_read_b128 v[0:3], v219 offset:15872
	ds_read_b128 v[4:7], v219 offset:15888
	ds_read_b128 v[8:11], v219 offset:15904
	ds_read_b128 v[12:15], v219 offset:15920
	ds_read_b128 v[18:21], v219 offset:15936
	ds_read_b128 v[22:25], v219 offset:15952
	ds_read_b128 v[26:29], v219 offset:15968
	ds_read_b128 v[30:33], v219 offset:15984
	ds_read_b128 v[34:37], v219 offset:16000
	ds_read_b128 v[38:41], v219 offset:16016
	ds_read_b128 v[42:45], v219 offset:16032
	v_fma_f32 v214, -v138, v68, v213
	v_fma_f32 v215, -v139, v69, 0
	v_fma_f32 v216, -v140, v70, 0
	v_fma_f32 v217, -v141, v71, 0
	v_fma_f32 v214, -v142, v72, v214
	v_fma_f32 v215, -v143, v73, v215
	v_fma_f32 v216, -v144, v74, v216
	v_fma_f32 v217, -v145, v75, v217
	v_fma_f32 v214, -v146, v76, v214
	v_fma_f32 v215, -v147, v77, v215
	v_fma_f32 v216, -v148, v78, v216
	v_fma_f32 v217, -v149, v79, v217
	v_fma_f32 v214, -v150, v80, v214
	v_fma_f32 v215, -v151, v81, v215
	v_fma_f32 v216, -v152, v82, v216
	v_fma_f32 v217, -v153, v83, v217
	v_fma_f32 v214, -v154, v84, v214
	v_fma_f32 v215, -v155, v85, v215
	v_fma_f32 v216, -v156, v86, v216
	v_fma_f32 v217, -v157, v87, v217
	v_fma_f32 v214, -v158, v88, v214
	v_fma_f32 v215, -v159, v89, v215
	v_fma_f32 v216, -v160, v90, v216
	v_fma_f32 v217, -v161, v91, v217
	s_waitcnt lgkmcnt(4)
	ds_read_b128 v[46:49], v219 offset:16048
	ds_read_b128 v[50:53], v219 offset:16064
	ds_read_b128 v[54:57], v219 offset:16080
	ds_read_b128 v[58:61], v219 offset:16096
	ds_read_b128 v[62:65], v219 offset:16112
	v_fma_f32 v214, -v162, v92, v214
	v_fma_f32 v215, -v163, v93, v215
	v_fma_f32 v216, -v164, v94, v216
	v_fma_f32 v217, -v165, v95, v217
	v_fma_f32 v214, -v166, v96, v214
	v_fma_f32 v215, -v167, v97, v215
	v_fma_f32 v216, -v168, v98, v216
	v_fma_f32 v217, -v169, v99, v217
	v_fma_f32 v214, -v170, v100, v214
	v_fma_f32 v215, -v171, v101, v215
	v_fma_f32 v216, -v172, v102, v216
	v_fma_f32 v217, -v173, v103, v217
	v_fma_f32 v214, -v174, v108, v214
	v_fma_f32 v215, -v175, v109, v215
	v_fma_f32 v216, -v176, v110, v216
	v_fma_f32 v217, -v177, v111, v217
	v_fma_f32 v214, -v178, v112, v214
	v_fma_f32 v215, -v179, v113, v215
	v_fma_f32 v216, -v180, v114, v216
	v_fma_f32 v217, -v181, v115, v217
	v_fma_f32 v214, -v182, v116, v214
	v_fma_f32 v215, -v183, v117, v215
	v_fma_f32 v216, -v184, v118, v216
	v_fma_f32 v217, -v185, v119, v217
	v_fma_f32 v214, -v186, v120, v214
	v_fma_f32 v215, -v187, v121, v215
	v_fma_f32 v216, -v188, v122, v216
	v_fma_f32 v217, -v189, v123, v217
	v_fma_f32 v214, -v190, v124, v214
	v_fma_f32 v215, -v191, v125, v215
	v_fma_f32 v216, -v192, v126, v216
	v_fma_f32 v217, -v193, v127, v217
	v_fma_f32 v214, -v194, v128, v214
	v_fma_f32 v215, -v195, v129, v215
	v_fma_f32 v216, -v196, v130, v216
	v_fma_f32 v217, -v197, v131, v217
	v_fma_f32 v214, -v208, v132, v214
	v_add_f32_e32 v214, v215, v214
	v_add_f32_e32 v215, v216, v217
	v_add_f32_e32 v209, v215, v214
	ds_write_b32 v218, v209 offset:63440
	s_waitcnt lgkmcnt(0)
	ds_read_b32 v213, v218 offset:65520
	ds_read_b128 v[68:71], v219 offset:16128
	ds_read_b128 v[72:75], v219 offset:16144
	ds_read_b128 v[76:79], v219 offset:16160
	ds_read_b128 v[80:83], v219 offset:16176
	ds_read_b128 v[84:87], v219 offset:16192
	ds_read_b128 v[88:91], v219 offset:16208
	ds_read_b128 v[92:95], v219 offset:16224
	ds_read_b128 v[96:99], v219 offset:16240
	ds_read_b128 v[100:103], v219 offset:16256
	ds_read_b128 v[108:111], v219 offset:16272
	ds_read_b128 v[112:115], v219 offset:16288
	v_fma_f32 v214, -v138, v0, v212
	v_fma_f32 v215, -v139, v1, 0
	v_fma_f32 v216, -v140, v2, 0
	v_fma_f32 v217, -v141, v3, 0
	v_fma_f32 v214, -v142, v4, v214
	v_fma_f32 v215, -v143, v5, v215
	v_fma_f32 v216, -v144, v6, v216
	v_fma_f32 v217, -v145, v7, v217
	v_fma_f32 v214, -v146, v8, v214
	v_fma_f32 v215, -v147, v9, v215
	v_fma_f32 v216, -v148, v10, v216
	v_fma_f32 v217, -v149, v11, v217
	v_fma_f32 v214, -v150, v12, v214
	v_fma_f32 v215, -v151, v13, v215
	v_fma_f32 v216, -v152, v14, v216
	v_fma_f32 v217, -v153, v15, v217
	v_fma_f32 v214, -v154, v18, v214
	v_fma_f32 v215, -v155, v19, v215
	v_fma_f32 v216, -v156, v20, v216
	v_fma_f32 v217, -v157, v21, v217
	v_fma_f32 v214, -v158, v22, v214
	v_fma_f32 v215, -v159, v23, v215
	v_fma_f32 v216, -v160, v24, v216
	v_fma_f32 v217, -v161, v25, v217
	s_waitcnt lgkmcnt(4)
	ds_read_b128 v[116:119], v219 offset:16304
	ds_read_b128 v[120:123], v219 offset:16320
	ds_read_b128 v[124:127], v219 offset:16336
	ds_read_b128 v[128:131], v219 offset:16352
	ds_read_b128 v[132:135], v219 offset:16368
	v_fma_f32 v214, -v162, v26, v214
	v_fma_f32 v215, -v163, v27, v215
	v_fma_f32 v216, -v164, v28, v216
	v_fma_f32 v217, -v165, v29, v217
	v_fma_f32 v214, -v166, v30, v214
	v_fma_f32 v215, -v167, v31, v215
	v_fma_f32 v216, -v168, v32, v216
	v_fma_f32 v217, -v169, v33, v217
	v_fma_f32 v214, -v170, v34, v214
	v_fma_f32 v215, -v171, v35, v215
	v_fma_f32 v216, -v172, v36, v216
	v_fma_f32 v217, -v173, v37, v217
	v_fma_f32 v214, -v174, v38, v214
	v_fma_f32 v215, -v175, v39, v215
	v_fma_f32 v216, -v176, v40, v216
	v_fma_f32 v217, -v177, v41, v217
	v_fma_f32 v214, -v178, v42, v214
	v_fma_f32 v215, -v179, v43, v215
	v_fma_f32 v216, -v180, v44, v216
	v_fma_f32 v217, -v181, v45, v217
	v_fma_f32 v214, -v182, v46, v214
	v_fma_f32 v215, -v183, v47, v215
	v_fma_f32 v216, -v184, v48, v216
	v_fma_f32 v217, -v185, v49, v217
	v_fma_f32 v214, -v186, v50, v214
	v_fma_f32 v215, -v187, v51, v215
	v_fma_f32 v216, -v188, v52, v216
	v_fma_f32 v217, -v189, v53, v217
	v_fma_f32 v214, -v190, v54, v214
	v_fma_f32 v215, -v191, v55, v215
	v_fma_f32 v216, -v192, v56, v216
	v_fma_f32 v217, -v193, v57, v217
	v_fma_f32 v214, -v194, v58, v214
	v_fma_f32 v215, -v195, v59, v215
	v_fma_f32 v216, -v196, v60, v216
	v_fma_f32 v217, -v197, v61, v217
	v_fma_f32 v214, -v208, v62, v214
	v_fma_f32 v215, -v209, v63, v215
	v_add_f32_e32 v214, v215, v214
	v_add_f32_e32 v215, v216, v217
	v_add_f32_e32 v210, v215, v214
	ds_write_b32 v218, v210 offset:64480
	s_waitcnt lgkmcnt(0)
	v_fma_f32 v214, -v138, v68, v213
	v_fma_f32 v215, -v139, v69, 0
	v_fma_f32 v216, -v140, v70, 0
	v_fma_f32 v217, -v141, v71, 0
	v_fma_f32 v214, -v142, v72, v214
	v_fma_f32 v215, -v143, v73, v215
	v_fma_f32 v216, -v144, v74, v216
	v_fma_f32 v217, -v145, v75, v217
	v_fma_f32 v214, -v146, v76, v214
	v_fma_f32 v215, -v147, v77, v215
	v_fma_f32 v216, -v148, v78, v216
	v_fma_f32 v217, -v149, v79, v217
	v_fma_f32 v214, -v150, v80, v214
	v_fma_f32 v215, -v151, v81, v215
	v_fma_f32 v216, -v152, v82, v216
	v_fma_f32 v217, -v153, v83, v217
	v_fma_f32 v214, -v154, v84, v214
	v_fma_f32 v215, -v155, v85, v215
	v_fma_f32 v216, -v156, v86, v216
	v_fma_f32 v217, -v157, v87, v217
	v_fma_f32 v214, -v158, v88, v214
	v_fma_f32 v215, -v159, v89, v215
	v_fma_f32 v216, -v160, v90, v216
	v_fma_f32 v217, -v161, v91, v217
	v_fma_f32 v214, -v162, v92, v214
	v_fma_f32 v215, -v163, v93, v215
	v_fma_f32 v216, -v164, v94, v216
	v_fma_f32 v217, -v165, v95, v217
	v_fma_f32 v214, -v166, v96, v214
	v_fma_f32 v215, -v167, v97, v215
	v_fma_f32 v216, -v168, v98, v216
	v_fma_f32 v217, -v169, v99, v217
	v_fma_f32 v214, -v170, v100, v214
	v_fma_f32 v215, -v171, v101, v215
	v_fma_f32 v216, -v172, v102, v216
	v_fma_f32 v217, -v173, v103, v217
	v_fma_f32 v214, -v174, v108, v214
	v_fma_f32 v215, -v175, v109, v215
	v_fma_f32 v216, -v176, v110, v216
	v_fma_f32 v217, -v177, v111, v217
	v_fma_f32 v214, -v178, v112, v214
	v_fma_f32 v215, -v179, v113, v215
	v_fma_f32 v216, -v180, v114, v216
	v_fma_f32 v217, -v181, v115, v217
	v_fma_f32 v214, -v182, v116, v214
	v_fma_f32 v215, -v183, v117, v215
	v_fma_f32 v216, -v184, v118, v216
	v_fma_f32 v217, -v185, v119, v217
	v_fma_f32 v214, -v186, v120, v214
	v_fma_f32 v215, -v187, v121, v215
	v_fma_f32 v216, -v188, v122, v216
	v_fma_f32 v217, -v189, v123, v217
	v_fma_f32 v214, -v190, v124, v214
	v_fma_f32 v215, -v191, v125, v215
	v_fma_f32 v216, -v192, v126, v216
	v_fma_f32 v217, -v193, v127, v217
	v_fma_f32 v214, -v194, v128, v214
	v_fma_f32 v215, -v195, v129, v215
	v_fma_f32 v216, -v196, v130, v216
	v_fma_f32 v217, -v197, v131, v217
	v_fma_f32 v214, -v208, v132, v214
	v_fma_f32 v215, -v209, v133, v215
	v_fma_f32 v216, -v210, v134, v216
	v_add_f32_e32 v214, v215, v214
	v_add_f32_e32 v215, v216, v217
	v_add_f32_e32 v211, v215, v214
	ds_write_b32 v218, v211 offset:65520
	s_branch .LBB0_759
